# in-proj tile walk: odd n-groups traverse the m-tiles backwards (activation tiles reused from L2 at group boundaries)
# baseline (speedup 1.0000x reference)
.LBB0_180:
	s_or_b64 exec, exec, s[0:1]
	v_readlane_b32 s0, v252, 1
	v_readlane_b32 s1, v252, 2
	s_mov_b32 s17, s23
	v_mov_b32_e32 v4, v222
	s_lshl_b32 s8, s16, 9
	s_andn2_b64 vcc, exec, s[0:1]
	s_mov_b32 s9, s23
	s_waitcnt lgkmcnt(0)
	s_barrier
	s_cbranch_vccnz .LBB0_488
	v_lshlrev_b32_e32 v2, 3, v4
	v_ashrrev_i32_e32 v6, 3, v4
	v_and_b32_e32 v2, 56, v2
	v_lshl_or_b32 v2, v6, 10, v2
	v_lshlrev_b32_e32 v7, 7, v6
	v_xor_b32_e32 v6, v6, v4
	v_lshlrev_b32_e32 v6, 4, v6
	s_mul_i32 s1, s16, 0x700000
	v_readlane_b32 s4, v253, 62
	v_and_b32_e32 v6, 0x70, v6
	s_mul_hi_u32 s0, s16, 0x700000
	s_add_u32 s66, s4, s1
	v_readlane_b32 s1, v253, 63
	v_add3_u32 v174, 32, v7, v6
	v_lshlrev_b32_e32 v6, 7, v4
	s_addc_u32 s67, s1, s0
	s_lshl_b64 s[0:1], s[8:9], 2
	v_and_b32_e32 v6, 0x2780, v6
	s_add_u32 s38, s30, s0
	v_and_b32_e32 v0, 15, v4
	v_add_u32_e32 v24, 32, v6
	v_ashrrev_i32_e32 v6, 1, v4
	s_movk_i32 s0, 0xffc0
	v_lshrrev_b32_e32 v1, 4, v4
	v_and_or_b32 v175, v6, s0, v0
	v_and_b32_e32 v6, 7, v4
	v_bitop3_b32 v1, v1, v6, 3 bitop3:0x6c
	v_lshl_add_u32 v0, v175, 7, 32
	v_lshlrev_b32_e32 v1, 4, v1
	s_addc_u32 s39, s31, s1
	v_bfe_u32 v5, v4, 4, 2
	v_and_b32_e32 v27, 64, v4
	v_add_u32_e32 v176, v24, v1
	v_add_u32_e32 v177, v0, v1
	v_xor_b32_e32 v1, 64, v1
	v_readlane_b32 s0, v252, 6
	v_add_u32_e32 v178, v24, v1
	v_add_u32_e32 v179, v0, v1
	v_lshlrev_b32_e32 v0, 1, v27
	v_lshlrev_b32_e32 v1, 3, v5
	v_lshlrev_b32_e32 v24, 4, v5
	v_mov_b32_e32 v25, v3
	v_readlane_b32 s1, v252, 7
	v_add3_u32 v180, 32, v0, v1
	s_movk_i32 s4, 0x110
	v_lshl_add_u64 v[0:1], s[0:1], 0, v[24:25]
	v_readlane_b32 s0, v252, 4
	v_readlane_b32 s1, v252, 5
	v_ashrrev_i32_e32 v181, 4, v4
	v_add_u32_e32 v6, 0x8000, v2
	v_lshl_add_u64 v[132:133], s[0:1], 0, v[24:25]
	v_lshlrev_b32_e32 v24, 4, v4
	v_and_b32_e32 v24, 0xf0, v24
	v_add_u32_e32 v25, 0x100, v4
	v_add_u32_e32 v26, 32, v24
	v_ashrrev_i32_e32 v182, 4, v25
	v_mad_u64_u32 v[136:137], s[0:1], v182, s4, v[26:27]
	v_add_u32_e32 v25, 0x200, v4
	v_ashrrev_i32_e32 v137, 4, v25
	v_mad_u64_u32 v[138:139], s[0:1], v137, s4, v[26:27]
	v_add_u32_e32 v25, 0x300, v4
	v_ashrrev_i32_e32 v139, 4, v25
	v_mad_u64_u32 v[140:141], s[0:1], v139, s4, v[26:27]
	v_add_u32_e32 v25, 0x400, v4
	v_ashrrev_i32_e32 v141, 4, v25
	v_mad_u64_u32 v[142:143], s[0:1], v141, s4, v[26:27]
	v_add_u32_e32 v25, 0x500, v4
	v_ashrrev_i32_e32 v143, 4, v25
	v_mad_u64_u32 v[144:145], s[0:1], v143, s4, v[26:27]
	v_add_u32_e32 v25, 0x600, v4
	v_ashrrev_i32_e32 v145, 4, v25
	v_mad_u64_u32 v[146:147], s[0:1], v145, s4, v[26:27]
	v_add_u32_e32 v4, 0x700, v4
	v_ashrrev_i32_e32 v147, 4, v4
	v_mov_b32_e32 v7, v3
	v_add_u32_e32 v8, 0x10000, v2
	v_mov_b32_e32 v9, v3
	v_add_u32_e32 v10, 0x18000, v2
	v_mov_b32_e32 v11, v3
	v_add_u32_e32 v12, 0x8040, v2
	v_mov_b32_e32 v13, v3
	v_add_u32_e32 v14, 0x10040, v2
	v_mov_b32_e32 v15, v3
	v_add_u32_e32 v16, 0x18040, v2
	v_mov_b32_e32 v17, v3
	v_add_u32_e32 v18, 0x8080, v2
	v_mov_b32_e32 v19, v3
	s_waitcnt vmcnt(12)
	v_add_u32_e32 v20, 0x10080, v2
	v_mov_b32_e32 v21, v3
	v_add_u32_e32 v22, 0x18080, v2
	v_mov_b32_e32 v23, v3
	v_mad_u64_u32 v[134:135], s[0:1], v181, s4, v[26:27]
	v_mad_u64_u32 v[148:149], s[0:1], v147, s4, v[26:27]
	v_mov_b32_e32 v25, v3
	v_mul_lo_u32 v135, v175, s4
	v_lshl_add_u64 v[150:151], s[24:25], 0, v[24:25]
	v_lshl_or_b32 v149, v5, 2, v27
	v_add_u32_e32 v183, 0x18100, v2
	v_lshlrev_b64 v[152:153], 1, v[2:3]
	v_lshlrev_b64 v[154:155], 1, v[6:7]
	v_lshlrev_b64 v[156:157], 1, v[8:9]
	v_lshlrev_b64 v[158:159], 1, v[10:11]
	v_lshlrev_b64 v[160:161], 1, v[12:13]
	v_lshlrev_b64 v[162:163], 1, v[14:15]
	v_lshlrev_b64 v[164:165], 1, v[16:17]
	v_lshlrev_b64 v[166:167], 1, v[18:19]
	v_lshlrev_b64 v[168:169], 1, v[20:21]
	v_lshlrev_b64 v[170:171], 1, v[22:23]
	v_readlane_b32 s36, v252, 3
	v_lshrrev_b32_e32 v4, 3, v222
	v_and_b32_e32 v5, 7, v222
	v_lshlrev_b32_e32 v5, 4, v5
	v_lshl_or_b32 v172, v4, 11, v5
	v_add_u32_e32 v173, 0x10000, v172
	v_add_u32_e32 v183, 0x20000, v172
	v_add_u32_e32 v2, 0x30000, v172
	s_bfe_u32 s0, s36, 0xf0001
	s_mul_i32 s0, s0, 0x89af
	s_lshr_b32 s0, s0, 22
	s_mul_i32 s1, s0, 0xee
	s_sub_i32 s1, s36, s1
	s_mul_i32 s4, s1, 37
	s_lshr_b32 s5, s4, 8
	s_sub_i32 s5, s1, s5
	s_bfe_u32 s5, s5, 0x70001
	s_bfe_u32 s4, s4, 0x80008
	s_add_i32 s5, s5, s4
	s_bfe_u32 s4, s5, 0x60002
	s_mul_i32 s5, s4, 7
	s_sub_i32 s1, s1, s5
	s_sub_i32 s5, 33, s4
	s_bitcmp1_b32 s0, 0
	s_cselect_b32 s4, s5, s4
	s_and_b32 s10, s1, 0xff
	s_mul_i32 s0, s0, 7
	s_add_i32 s10, s10, s0
	v_readlane_b32 s0, v252, 8
	s_add_i32 s42, s0, s4
	s_lshl_b32 s22, s10, 7
	s_lshl_b32 s0, s10, 18
	s_add_u32 s0, s66, s0
	s_addc_u32 s1, s67, 0
	s_lshl_b32 s4, s42, 18
	s_add_u32 s4, s20, s4
	s_addc_u32 s5, s21, 0
	global_load_dwordx4 v[84:87], v172, s[0:1]
	global_load_dwordx4 v[100:103], v172, s[4:5]
	global_load_dwordx4 v[88:91], v173, s[0:1]
	global_load_dwordx4 v[104:107], v173, s[4:5]
	global_load_dwordx4 v[92:95], v183, s[0:1]
	global_load_dwordx4 v[108:111], v183, s[4:5]
	global_load_dwordx4 v[96:99], v2, s[0:1]
	global_load_dwordx4 v[112:115], v2, s[4:5]
	global_load_dwordx4 v[184:187], v172, s[0:1] offset:128
	global_load_dwordx4 v[200:203], v172, s[4:5] offset:128
	global_load_dwordx4 v[188:191], v173, s[0:1] offset:128
	global_load_dwordx4 v[204:207], v173, s[4:5] offset:128
	global_load_dwordx4 v[192:195], v183, s[0:1] offset:128
	global_load_dwordx4 v[208:211], v183, s[4:5] offset:128
	global_load_dwordx4 v[196:199], v2, s[0:1] offset:128
	global_load_dwordx4 v[212:215], v2, s[4:5] offset:128
	s_waitcnt vmcnt(8)
	s_branch .Lg0_pro

.LBB0_184:
	s_bfe_u32 s0, s36, 0xf0001
	s_mul_i32 s0, s0, 0x89af
	s_lshr_b32 s0, s0, 22
	s_mul_i32 s1, s0, 0xee
	s_sub_i32 s1, s36, s1
	s_mul_i32 s4, s1, 37
	s_lshr_b32 s5, s4, 8
	s_sub_i32 s5, s1, s5
	s_bfe_u32 s5, s5, 0x70001
	s_bfe_u32 s4, s4, 0x80008
	s_add_i32 s5, s5, s4
	s_bfe_u32 s4, s5, 0x60002
	s_mul_i32 s5, s4, 7
	s_sub_i32 s1, s1, s5
	s_sub_i32 s5, 33, s4
	s_bitcmp1_b32 s0, 0
	s_cselect_b32 s4, s5, s4
	s_and_b32 s10, s1, 0xff
	s_mul_i32 s0, s0, 7
	s_add_i32 s10, s10, s0
	v_readlane_b32 s0, v252, 8
	s_lshl_b32 s22, s10, 7
	s_add_i32 s42, s0, s4
	s_lshl_b32 s0, s10, 18
	s_add_u32 s0, s66, s0
	s_addc_u32 s1, s67, 0
	s_lshl_b32 s4, s42, 18
	s_add_u32 s4, s20, s4
	s_addc_u32 s5, s21, 0
	v_add_u32_e32 v2, 0x30000, v172
	s_waitcnt vmcnt(16)
.Lg0_pro:
	ds_write_b128 v174, v[84:87]
	ds_write_b128 v174, v[100:103] offset:32768
	ds_write_b128 v174, v[88:91] offset:4096
	ds_write_b128 v174, v[104:107] offset:36864
	ds_write_b128 v174, v[92:95] offset:8192
	ds_write_b128 v174, v[108:111] offset:40960
	ds_write_b128 v174, v[96:99] offset:12288
	ds_write_b128 v174, v[112:115] offset:45056
	global_load_dwordx4 v[84:87], v172, s[0:1] offset:256
	global_load_dwordx4 v[100:103], v172, s[4:5] offset:256
	global_load_dwordx4 v[88:91], v173, s[0:1] offset:256
	global_load_dwordx4 v[104:107], v173, s[4:5] offset:256
	global_load_dwordx4 v[92:95], v183, s[0:1] offset:256
	global_load_dwordx4 v[108:111], v183, s[4:5] offset:256
	global_load_dwordx4 v[96:99], v2, s[0:1] offset:256
	global_load_dwordx4 v[112:115], v2, s[4:5] offset:256
	s_waitcnt lgkmcnt(0)
	s_barrier
	ds_read_b128 v[68:71], v176
	ds_read_b128 v[116:119], v177 offset:32768
	ds_read_b128 v[72:75], v176 offset:2048
	ds_read_b128 v[120:123], v177 offset:34816
	ds_read_b128 v[76:79], v176 offset:4096
	ds_read_b128 v[124:127], v177 offset:36864
	ds_read_b128 v[80:83], v176 offset:6144
	ds_read_b128 v[128:131], v177 offset:38912
	s_waitcnt lgkmcnt(0)
	v_mfma_f32_16x16x32_bf16 v[64:67], v[68:71], v[116:119], 0
	ds_read_b128 v[152:155], v178
	s_waitcnt vmcnt(8)
	ds_write_b128 v174, v[184:187] offset:16384
	v_mfma_f32_16x16x32_bf16 v[48:51], v[68:71], v[120:123], 0
	ds_read_b128 v[168:171], v179 offset:32768
	ds_write_b128 v174, v[200:203] offset:49152
	v_mfma_f32_16x16x32_bf16 v[32:35], v[68:71], v[124:127], 0
	ds_read_b128 v[156:159], v178 offset:2048
	ds_write_b128 v174, v[188:191] offset:20480
	v_mfma_f32_16x16x32_bf16 v[16:19], v[68:71], v[128:131], 0
	ds_read_b128 v[240:243], v179 offset:34816
	ds_write_b128 v174, v[204:207] offset:53248
	v_mfma_f32_16x16x32_bf16 v[60:63], v[72:75], v[116:119], 0
	ds_read_b128 v[160:163], v178 offset:4096
	ds_write_b128 v174, v[192:195] offset:24576
	v_mfma_f32_16x16x32_bf16 v[44:47], v[72:75], v[120:123], 0
	ds_read_b128 v[244:247], v179 offset:36864
	ds_write_b128 v174, v[208:211] offset:57344
	v_mfma_f32_16x16x32_bf16 v[28:31], v[72:75], v[124:127], 0
	ds_read_b128 v[164:167], v178 offset:6144
	ds_write_b128 v174, v[196:199] offset:28672
	v_mfma_f32_16x16x32_bf16 v[12:15], v[72:75], v[128:131], 0
	ds_read_b128 v[248:251], v179 offset:38912
	ds_write_b128 v174, v[212:215] offset:61440
	v_mfma_f32_16x16x32_bf16 v[56:59], v[76:79], v[116:119], 0
	global_load_dwordx4 v[184:187], v172, s[0:1] offset:384
	v_mfma_f32_16x16x32_bf16 v[40:43], v[76:79], v[120:123], 0
	global_load_dwordx4 v[200:203], v172, s[4:5] offset:384
	v_mfma_f32_16x16x32_bf16 v[24:27], v[76:79], v[124:127], 0
	global_load_dwordx4 v[188:191], v173, s[0:1] offset:384
	v_mfma_f32_16x16x32_bf16 v[4:7], v[76:79], v[128:131], 0
	global_load_dwordx4 v[204:207], v173, s[4:5] offset:384
	v_mfma_f32_16x16x32_bf16 v[52:55], v[80:83], v[116:119], 0
	global_load_dwordx4 v[192:195], v183, s[0:1] offset:384
	v_mfma_f32_16x16x32_bf16 v[36:39], v[80:83], v[120:123], 0
	global_load_dwordx4 v[208:211], v183, s[4:5] offset:384
	v_mfma_f32_16x16x32_bf16 v[20:23], v[80:83], v[124:127], 0
	global_load_dwordx4 v[196:199], v2, s[0:1] offset:384
	v_mfma_f32_16x16x32_bf16 v[8:11], v[80:83], v[128:131], 0
	global_load_dwordx4 v[212:215], v2, s[4:5] offset:384
	s_waitcnt lgkmcnt(0)
	s_barrier
	v_mfma_f32_16x16x32_bf16 v[64:67], v[152:155], v[168:171], v[64:67]
	ds_read_b128 v[68:71], v176 offset:16384
	v_mfma_f32_16x16x32_bf16 v[48:51], v[152:155], v[240:243], v[48:51]
	ds_read_b128 v[116:119], v177 offset:49152
	v_mfma_f32_16x16x32_bf16 v[32:35], v[152:155], v[244:247], v[32:35]
	ds_read_b128 v[72:75], v176 offset:18432
	v_mfma_f32_16x16x32_bf16 v[16:19], v[152:155], v[248:251], v[16:19]
	ds_read_b128 v[120:123], v177 offset:51200
	v_mfma_f32_16x16x32_bf16 v[60:63], v[156:159], v[168:171], v[60:63]
	ds_read_b128 v[76:79], v176 offset:20480
	v_mfma_f32_16x16x32_bf16 v[44:47], v[156:159], v[240:243], v[44:47]
	ds_read_b128 v[124:127], v177 offset:53248
	v_mfma_f32_16x16x32_bf16 v[28:31], v[156:159], v[244:247], v[28:31]
	ds_read_b128 v[80:83], v176 offset:22528
	v_mfma_f32_16x16x32_bf16 v[12:15], v[156:159], v[248:251], v[12:15]
	ds_read_b128 v[128:131], v177 offset:55296
	v_mfma_f32_16x16x32_bf16 v[56:59], v[160:163], v[168:171], v[56:59]
	v_mfma_f32_16x16x32_bf16 v[40:43], v[160:163], v[240:243], v[40:43]
	v_mfma_f32_16x16x32_bf16 v[24:27], v[160:163], v[244:247], v[24:27]
	v_mfma_f32_16x16x32_bf16 v[4:7], v[160:163], v[248:251], v[4:7]
	v_mfma_f32_16x16x32_bf16 v[52:55], v[164:167], v[168:171], v[52:55]
	v_mfma_f32_16x16x32_bf16 v[36:39], v[164:167], v[240:243], v[36:39]
	v_mfma_f32_16x16x32_bf16 v[20:23], v[164:167], v[244:247], v[20:23]
	v_mfma_f32_16x16x32_bf16 v[8:11], v[164:167], v[248:251], v[8:11]
	s_waitcnt lgkmcnt(0)
	v_mfma_f32_16x16x32_bf16 v[64:67], v[68:71], v[116:119], v[64:67]
	ds_read_b128 v[152:155], v178 offset:16384
	s_waitcnt vmcnt(8)
	ds_write_b128 v174, v[84:87]
	v_mfma_f32_16x16x32_bf16 v[48:51], v[68:71], v[120:123], v[48:51]
	ds_read_b128 v[168:171], v179 offset:49152
	ds_write_b128 v174, v[100:103] offset:32768
	v_mfma_f32_16x16x32_bf16 v[32:35], v[68:71], v[124:127], v[32:35]
	ds_read_b128 v[156:159], v178 offset:18432
	ds_write_b128 v174, v[88:91] offset:4096
	v_mfma_f32_16x16x32_bf16 v[16:19], v[68:71], v[128:131], v[16:19]
	ds_read_b128 v[240:243], v179 offset:51200
	ds_write_b128 v174, v[104:107] offset:36864
	v_mfma_f32_16x16x32_bf16 v[60:63], v[72:75], v[116:119], v[60:63]
	ds_read_b128 v[160:163], v178 offset:20480
	ds_write_b128 v174, v[92:95] offset:8192
	v_mfma_f32_16x16x32_bf16 v[44:47], v[72:75], v[120:123], v[44:47]
	ds_read_b128 v[244:247], v179 offset:53248
	ds_write_b128 v174, v[108:111] offset:40960
	v_mfma_f32_16x16x32_bf16 v[28:31], v[72:75], v[124:127], v[28:31]
	ds_read_b128 v[164:167], v178 offset:22528
	ds_write_b128 v174, v[96:99] offset:12288
	v_mfma_f32_16x16x32_bf16 v[12:15], v[72:75], v[128:131], v[12:15]
	ds_read_b128 v[248:251], v179 offset:55296
	ds_write_b128 v174, v[112:115] offset:45056
	v_mfma_f32_16x16x32_bf16 v[56:59], v[76:79], v[116:119], v[56:59]
	global_load_dwordx4 v[84:87], v172, s[0:1] offset:512
	v_mfma_f32_16x16x32_bf16 v[40:43], v[76:79], v[120:123], v[40:43]
	global_load_dwordx4 v[100:103], v172, s[4:5] offset:512
	v_mfma_f32_16x16x32_bf16 v[24:27], v[76:79], v[124:127], v[24:27]
	global_load_dwordx4 v[88:91], v173, s[0:1] offset:512
	v_mfma_f32_16x16x32_bf16 v[4:7], v[76:79], v[128:131], v[4:7]
	global_load_dwordx4 v[104:107], v173, s[4:5] offset:512
	v_mfma_f32_16x16x32_bf16 v[52:55], v[80:83], v[116:119], v[52:55]
	global_load_dwordx4 v[92:95], v183, s[0:1] offset:512
	v_mfma_f32_16x16x32_bf16 v[36:39], v[80:83], v[120:123], v[36:39]
	global_load_dwordx4 v[108:111], v183, s[4:5] offset:512
	v_mfma_f32_16x16x32_bf16 v[20:23], v[80:83], v[124:127], v[20:23]
	global_load_dwordx4 v[96:99], v2, s[0:1] offset:512
	v_mfma_f32_16x16x32_bf16 v[8:11], v[80:83], v[128:131], v[8:11]
	global_load_dwordx4 v[112:115], v2, s[4:5] offset:512
	s_waitcnt lgkmcnt(0)
	s_barrier
	v_mfma_f32_16x16x32_bf16 v[64:67], v[152:155], v[168:171], v[64:67]
	ds_read_b128 v[68:71], v176
	v_mfma_f32_16x16x32_bf16 v[48:51], v[152:155], v[240:243], v[48:51]
	ds_read_b128 v[116:119], v177 offset:32768
	v_mfma_f32_16x16x32_bf16 v[32:35], v[152:155], v[244:247], v[32:35]
	ds_read_b128 v[72:75], v176 offset:2048
	v_mfma_f32_16x16x32_bf16 v[16:19], v[152:155], v[248:251], v[16:19]
	ds_read_b128 v[120:123], v177 offset:34816
	v_mfma_f32_16x16x32_bf16 v[60:63], v[156:159], v[168:171], v[60:63]
	ds_read_b128 v[76:79], v176 offset:4096
	v_mfma_f32_16x16x32_bf16 v[44:47], v[156:159], v[240:243], v[44:47]
	ds_read_b128 v[124:127], v177 offset:36864
	v_mfma_f32_16x16x32_bf16 v[28:31], v[156:159], v[244:247], v[28:31]
	ds_read_b128 v[80:83], v176 offset:6144
	v_mfma_f32_16x16x32_bf16 v[12:15], v[156:159], v[248:251], v[12:15]
	ds_read_b128 v[128:131], v177 offset:38912
	v_mfma_f32_16x16x32_bf16 v[56:59], v[160:163], v[168:171], v[56:59]
	v_mfma_f32_16x16x32_bf16 v[40:43], v[160:163], v[240:243], v[40:43]
	v_mfma_f32_16x16x32_bf16 v[24:27], v[160:163], v[244:247], v[24:27]
	v_mfma_f32_16x16x32_bf16 v[4:7], v[160:163], v[248:251], v[4:7]
	v_mfma_f32_16x16x32_bf16 v[52:55], v[164:167], v[168:171], v[52:55]
	v_mfma_f32_16x16x32_bf16 v[36:39], v[164:167], v[240:243], v[36:39]
	v_mfma_f32_16x16x32_bf16 v[20:23], v[164:167], v[244:247], v[20:23]
	v_mfma_f32_16x16x32_bf16 v[8:11], v[164:167], v[248:251], v[8:11]
	s_waitcnt lgkmcnt(0)
	v_mfma_f32_16x16x32_bf16 v[64:67], v[68:71], v[116:119], v[64:67]
	ds_read_b128 v[152:155], v178
	s_waitcnt vmcnt(8)
	ds_write_b128 v174, v[184:187] offset:16384
	v_mfma_f32_16x16x32_bf16 v[48:51], v[68:71], v[120:123], v[48:51]
	ds_read_b128 v[168:171], v179 offset:32768
	ds_write_b128 v174, v[200:203] offset:49152
	v_mfma_f32_16x16x32_bf16 v[32:35], v[68:71], v[124:127], v[32:35]
	ds_read_b128 v[156:159], v178 offset:2048
	ds_write_b128 v174, v[188:191] offset:20480
	v_mfma_f32_16x16x32_bf16 v[16:19], v[68:71], v[128:131], v[16:19]
	ds_read_b128 v[240:243], v179 offset:34816
	ds_write_b128 v174, v[204:207] offset:53248
	v_mfma_f32_16x16x32_bf16 v[60:63], v[72:75], v[116:119], v[60:63]
	ds_read_b128 v[160:163], v178 offset:4096
	ds_write_b128 v174, v[192:195] offset:24576
	v_mfma_f32_16x16x32_bf16 v[44:47], v[72:75], v[120:123], v[44:47]
	ds_read_b128 v[244:247], v179 offset:36864
	ds_write_b128 v174, v[208:211] offset:57344
	v_mfma_f32_16x16x32_bf16 v[28:31], v[72:75], v[124:127], v[28:31]
	ds_read_b128 v[164:167], v178 offset:6144
	ds_write_b128 v174, v[196:199] offset:28672
	v_mfma_f32_16x16x32_bf16 v[12:15], v[72:75], v[128:131], v[12:15]
	ds_read_b128 v[248:251], v179 offset:38912
	ds_write_b128 v174, v[212:215] offset:61440
	v_mfma_f32_16x16x32_bf16 v[56:59], v[76:79], v[116:119], v[56:59]
	global_load_dwordx4 v[184:187], v172, s[0:1] offset:640
	v_mfma_f32_16x16x32_bf16 v[40:43], v[76:79], v[120:123], v[40:43]
	global_load_dwordx4 v[200:203], v172, s[4:5] offset:640
	v_mfma_f32_16x16x32_bf16 v[24:27], v[76:79], v[124:127], v[24:27]
	global_load_dwordx4 v[188:191], v173, s[0:1] offset:640
	v_mfma_f32_16x16x32_bf16 v[4:7], v[76:79], v[128:131], v[4:7]
	global_load_dwordx4 v[204:207], v173, s[4:5] offset:640
	v_mfma_f32_16x16x32_bf16 v[52:55], v[80:83], v[116:119], v[52:55]
	global_load_dwordx4 v[192:195], v183, s[0:1] offset:640
	v_mfma_f32_16x16x32_bf16 v[36:39], v[80:83], v[120:123], v[36:39]
	global_load_dwordx4 v[208:211], v183, s[4:5] offset:640
	v_mfma_f32_16x16x32_bf16 v[20:23], v[80:83], v[124:127], v[20:23]
	global_load_dwordx4 v[196:199], v2, s[0:1] offset:640
	v_mfma_f32_16x16x32_bf16 v[8:11], v[80:83], v[128:131], v[8:11]
	global_load_dwordx4 v[212:215], v2, s[4:5] offset:640
	s_waitcnt lgkmcnt(0)
	s_barrier
	v_mfma_f32_16x16x32_bf16 v[64:67], v[152:155], v[168:171], v[64:67]
	ds_read_b128 v[68:71], v176 offset:16384
	v_mfma_f32_16x16x32_bf16 v[48:51], v[152:155], v[240:243], v[48:51]
	ds_read_b128 v[116:119], v177 offset:49152
	v_mfma_f32_16x16x32_bf16 v[32:35], v[152:155], v[244:247], v[32:35]
	ds_read_b128 v[72:75], v176 offset:18432
	v_mfma_f32_16x16x32_bf16 v[16:19], v[152:155], v[248:251], v[16:19]
	ds_read_b128 v[120:123], v177 offset:51200
	v_mfma_f32_16x16x32_bf16 v[60:63], v[156:159], v[168:171], v[60:63]
	ds_read_b128 v[76:79], v176 offset:20480
	v_mfma_f32_16x16x32_bf16 v[44:47], v[156:159], v[240:243], v[44:47]
	ds_read_b128 v[124:127], v177 offset:53248
	v_mfma_f32_16x16x32_bf16 v[28:31], v[156:159], v[244:247], v[28:31]
	ds_read_b128 v[80:83], v176 offset:22528
	v_mfma_f32_16x16x32_bf16 v[12:15], v[156:159], v[248:251], v[12:15]
	ds_read_b128 v[128:131], v177 offset:55296
	v_mfma_f32_16x16x32_bf16 v[56:59], v[160:163], v[168:171], v[56:59]
	v_mfma_f32_16x16x32_bf16 v[40:43], v[160:163], v[240:243], v[40:43]
	v_mfma_f32_16x16x32_bf16 v[24:27], v[160:163], v[244:247], v[24:27]
	v_mfma_f32_16x16x32_bf16 v[4:7], v[160:163], v[248:251], v[4:7]
	v_mfma_f32_16x16x32_bf16 v[52:55], v[164:167], v[168:171], v[52:55]
	v_mfma_f32_16x16x32_bf16 v[36:39], v[164:167], v[240:243], v[36:39]
	v_mfma_f32_16x16x32_bf16 v[20:23], v[164:167], v[244:247], v[20:23]
	v_mfma_f32_16x16x32_bf16 v[8:11], v[164:167], v[248:251], v[8:11]
	s_waitcnt lgkmcnt(0)
	v_mfma_f32_16x16x32_bf16 v[64:67], v[68:71], v[116:119], v[64:67]
	ds_read_b128 v[152:155], v178 offset:16384
	s_waitcnt vmcnt(8)
	ds_write_b128 v174, v[84:87]
	v_mfma_f32_16x16x32_bf16 v[48:51], v[68:71], v[120:123], v[48:51]
	ds_read_b128 v[168:171], v179 offset:49152
	ds_write_b128 v174, v[100:103] offset:32768
	v_mfma_f32_16x16x32_bf16 v[32:35], v[68:71], v[124:127], v[32:35]
	ds_read_b128 v[156:159], v178 offset:18432
	ds_write_b128 v174, v[88:91] offset:4096
	v_mfma_f32_16x16x32_bf16 v[16:19], v[68:71], v[128:131], v[16:19]
	ds_read_b128 v[240:243], v179 offset:51200
	ds_write_b128 v174, v[104:107] offset:36864
	v_mfma_f32_16x16x32_bf16 v[60:63], v[72:75], v[116:119], v[60:63]
	ds_read_b128 v[160:163], v178 offset:20480
	ds_write_b128 v174, v[92:95] offset:8192
	v_mfma_f32_16x16x32_bf16 v[44:47], v[72:75], v[120:123], v[44:47]
	ds_read_b128 v[244:247], v179 offset:53248
	ds_write_b128 v174, v[108:111] offset:40960
	v_mfma_f32_16x16x32_bf16 v[28:31], v[72:75], v[124:127], v[28:31]
	ds_read_b128 v[164:167], v178 offset:22528
	ds_write_b128 v174, v[96:99] offset:12288
	v_mfma_f32_16x16x32_bf16 v[12:15], v[72:75], v[128:131], v[12:15]
	ds_read_b128 v[248:251], v179 offset:55296
	ds_write_b128 v174, v[112:115] offset:45056
	v_mfma_f32_16x16x32_bf16 v[56:59], v[76:79], v[116:119], v[56:59]
	global_load_dwordx4 v[84:87], v172, s[0:1] offset:768
	v_mfma_f32_16x16x32_bf16 v[40:43], v[76:79], v[120:123], v[40:43]
	global_load_dwordx4 v[100:103], v172, s[4:5] offset:768
	v_mfma_f32_16x16x32_bf16 v[24:27], v[76:79], v[124:127], v[24:27]
	global_load_dwordx4 v[88:91], v173, s[0:1] offset:768
	v_mfma_f32_16x16x32_bf16 v[4:7], v[76:79], v[128:131], v[4:7]
	global_load_dwordx4 v[104:107], v173, s[4:5] offset:768
	v_mfma_f32_16x16x32_bf16 v[52:55], v[80:83], v[116:119], v[52:55]
	global_load_dwordx4 v[92:95], v183, s[0:1] offset:768
	v_mfma_f32_16x16x32_bf16 v[36:39], v[80:83], v[120:123], v[36:39]
	global_load_dwordx4 v[108:111], v183, s[4:5] offset:768
	v_mfma_f32_16x16x32_bf16 v[20:23], v[80:83], v[124:127], v[20:23]
	global_load_dwordx4 v[96:99], v2, s[0:1] offset:768
	v_mfma_f32_16x16x32_bf16 v[8:11], v[80:83], v[128:131], v[8:11]
	global_load_dwordx4 v[112:115], v2, s[4:5] offset:768
	s_waitcnt lgkmcnt(0)
	s_barrier
	v_mfma_f32_16x16x32_bf16 v[64:67], v[152:155], v[168:171], v[64:67]
	ds_read_b128 v[68:71], v176
	v_mfma_f32_16x16x32_bf16 v[48:51], v[152:155], v[240:243], v[48:51]
	ds_read_b128 v[116:119], v177 offset:32768
	v_mfma_f32_16x16x32_bf16 v[32:35], v[152:155], v[244:247], v[32:35]
	ds_read_b128 v[72:75], v176 offset:2048
	v_mfma_f32_16x16x32_bf16 v[16:19], v[152:155], v[248:251], v[16:19]
	ds_read_b128 v[120:123], v177 offset:34816
	v_mfma_f32_16x16x32_bf16 v[60:63], v[156:159], v[168:171], v[60:63]
	ds_read_b128 v[76:79], v176 offset:4096
	v_mfma_f32_16x16x32_bf16 v[44:47], v[156:159], v[240:243], v[44:47]
	ds_read_b128 v[124:127], v177 offset:36864
	v_mfma_f32_16x16x32_bf16 v[28:31], v[156:159], v[244:247], v[28:31]
	ds_read_b128 v[80:83], v176 offset:6144
	v_mfma_f32_16x16x32_bf16 v[12:15], v[156:159], v[248:251], v[12:15]
	ds_read_b128 v[128:131], v177 offset:38912
	v_mfma_f32_16x16x32_bf16 v[56:59], v[160:163], v[168:171], v[56:59]
	v_mfma_f32_16x16x32_bf16 v[40:43], v[160:163], v[240:243], v[40:43]
	v_mfma_f32_16x16x32_bf16 v[24:27], v[160:163], v[244:247], v[24:27]
	v_mfma_f32_16x16x32_bf16 v[4:7], v[160:163], v[248:251], v[4:7]
	v_mfma_f32_16x16x32_bf16 v[52:55], v[164:167], v[168:171], v[52:55]
	v_mfma_f32_16x16x32_bf16 v[36:39], v[164:167], v[240:243], v[36:39]
	v_mfma_f32_16x16x32_bf16 v[20:23], v[164:167], v[244:247], v[20:23]
	v_mfma_f32_16x16x32_bf16 v[8:11], v[164:167], v[248:251], v[8:11]
	s_waitcnt lgkmcnt(0)
	v_mfma_f32_16x16x32_bf16 v[64:67], v[68:71], v[116:119], v[64:67]
	ds_read_b128 v[152:155], v178
	s_waitcnt vmcnt(8)
	ds_write_b128 v174, v[184:187] offset:16384
	v_mfma_f32_16x16x32_bf16 v[48:51], v[68:71], v[120:123], v[48:51]
	ds_read_b128 v[168:171], v179 offset:32768
	ds_write_b128 v174, v[200:203] offset:49152
	v_mfma_f32_16x16x32_bf16 v[32:35], v[68:71], v[124:127], v[32:35]
	ds_read_b128 v[156:159], v178 offset:2048
	ds_write_b128 v174, v[188:191] offset:20480
	v_mfma_f32_16x16x32_bf16 v[16:19], v[68:71], v[128:131], v[16:19]
	ds_read_b128 v[240:243], v179 offset:34816
	ds_write_b128 v174, v[204:207] offset:53248
	v_mfma_f32_16x16x32_bf16 v[60:63], v[72:75], v[116:119], v[60:63]
	ds_read_b128 v[160:163], v178 offset:4096
	ds_write_b128 v174, v[192:195] offset:24576
	v_mfma_f32_16x16x32_bf16 v[44:47], v[72:75], v[120:123], v[44:47]
	ds_read_b128 v[244:247], v179 offset:36864
	ds_write_b128 v174, v[208:211] offset:57344
	v_mfma_f32_16x16x32_bf16 v[28:31], v[72:75], v[124:127], v[28:31]
	ds_read_b128 v[164:167], v178 offset:6144
	ds_write_b128 v174, v[196:199] offset:28672
	v_mfma_f32_16x16x32_bf16 v[12:15], v[72:75], v[128:131], v[12:15]
	ds_read_b128 v[248:251], v179 offset:38912
	ds_write_b128 v174, v[212:215] offset:61440
	v_mfma_f32_16x16x32_bf16 v[56:59], v[76:79], v[116:119], v[56:59]
	global_load_dwordx4 v[184:187], v172, s[0:1] offset:896
	v_mfma_f32_16x16x32_bf16 v[40:43], v[76:79], v[120:123], v[40:43]
	global_load_dwordx4 v[200:203], v172, s[4:5] offset:896
	v_mfma_f32_16x16x32_bf16 v[24:27], v[76:79], v[124:127], v[24:27]
	global_load_dwordx4 v[188:191], v173, s[0:1] offset:896
	v_mfma_f32_16x16x32_bf16 v[4:7], v[76:79], v[128:131], v[4:7]
	global_load_dwordx4 v[204:207], v173, s[4:5] offset:896
	v_mfma_f32_16x16x32_bf16 v[52:55], v[80:83], v[116:119], v[52:55]
	global_load_dwordx4 v[192:195], v183, s[0:1] offset:896
	v_mfma_f32_16x16x32_bf16 v[36:39], v[80:83], v[120:123], v[36:39]
	global_load_dwordx4 v[208:211], v183, s[4:5] offset:896
	v_mfma_f32_16x16x32_bf16 v[20:23], v[80:83], v[124:127], v[20:23]
	global_load_dwordx4 v[196:199], v2, s[0:1] offset:896
	v_mfma_f32_16x16x32_bf16 v[8:11], v[80:83], v[128:131], v[8:11]
	global_load_dwordx4 v[212:215], v2, s[4:5] offset:896
	s_waitcnt lgkmcnt(0)
	s_barrier
	v_mfma_f32_16x16x32_bf16 v[64:67], v[152:155], v[168:171], v[64:67]
	ds_read_b128 v[68:71], v176 offset:16384
	v_mfma_f32_16x16x32_bf16 v[48:51], v[152:155], v[240:243], v[48:51]
	ds_read_b128 v[116:119], v177 offset:49152
	v_mfma_f32_16x16x32_bf16 v[32:35], v[152:155], v[244:247], v[32:35]
	ds_read_b128 v[72:75], v176 offset:18432
	v_mfma_f32_16x16x32_bf16 v[16:19], v[152:155], v[248:251], v[16:19]
	ds_read_b128 v[120:123], v177 offset:51200
	v_mfma_f32_16x16x32_bf16 v[60:63], v[156:159], v[168:171], v[60:63]
	ds_read_b128 v[76:79], v176 offset:20480
	v_mfma_f32_16x16x32_bf16 v[44:47], v[156:159], v[240:243], v[44:47]
	ds_read_b128 v[124:127], v177 offset:53248
	v_mfma_f32_16x16x32_bf16 v[28:31], v[156:159], v[244:247], v[28:31]
	ds_read_b128 v[80:83], v176 offset:22528
	v_mfma_f32_16x16x32_bf16 v[12:15], v[156:159], v[248:251], v[12:15]
	ds_read_b128 v[128:131], v177 offset:55296
	v_mfma_f32_16x16x32_bf16 v[56:59], v[160:163], v[168:171], v[56:59]
	v_mfma_f32_16x16x32_bf16 v[40:43], v[160:163], v[240:243], v[40:43]
	v_mfma_f32_16x16x32_bf16 v[24:27], v[160:163], v[244:247], v[24:27]
	v_mfma_f32_16x16x32_bf16 v[4:7], v[160:163], v[248:251], v[4:7]
	v_mfma_f32_16x16x32_bf16 v[52:55], v[164:167], v[168:171], v[52:55]
	v_mfma_f32_16x16x32_bf16 v[36:39], v[164:167], v[240:243], v[36:39]
	v_mfma_f32_16x16x32_bf16 v[20:23], v[164:167], v[244:247], v[20:23]
	v_mfma_f32_16x16x32_bf16 v[8:11], v[164:167], v[248:251], v[8:11]
	s_waitcnt lgkmcnt(0)
	v_mfma_f32_16x16x32_bf16 v[64:67], v[68:71], v[116:119], v[64:67]
	ds_read_b128 v[152:155], v178 offset:16384
	s_waitcnt vmcnt(8)
	ds_write_b128 v174, v[84:87]
	v_mfma_f32_16x16x32_bf16 v[48:51], v[68:71], v[120:123], v[48:51]
	ds_read_b128 v[168:171], v179 offset:49152
	ds_write_b128 v174, v[100:103] offset:32768
	v_mfma_f32_16x16x32_bf16 v[32:35], v[68:71], v[124:127], v[32:35]
	ds_read_b128 v[156:159], v178 offset:18432
	ds_write_b128 v174, v[88:91] offset:4096
	v_mfma_f32_16x16x32_bf16 v[16:19], v[68:71], v[128:131], v[16:19]
	ds_read_b128 v[240:243], v179 offset:51200
	ds_write_b128 v174, v[104:107] offset:36864
	v_mfma_f32_16x16x32_bf16 v[60:63], v[72:75], v[116:119], v[60:63]
	ds_read_b128 v[160:163], v178 offset:20480
	ds_write_b128 v174, v[92:95] offset:8192
	v_mfma_f32_16x16x32_bf16 v[44:47], v[72:75], v[120:123], v[44:47]
	ds_read_b128 v[244:247], v179 offset:53248
	ds_write_b128 v174, v[108:111] offset:40960
	v_mfma_f32_16x16x32_bf16 v[28:31], v[72:75], v[124:127], v[28:31]
	ds_read_b128 v[164:167], v178 offset:22528
	ds_write_b128 v174, v[96:99] offset:12288
	v_mfma_f32_16x16x32_bf16 v[12:15], v[72:75], v[128:131], v[12:15]
	ds_read_b128 v[248:251], v179 offset:55296
	ds_write_b128 v174, v[112:115] offset:45056
	v_mfma_f32_16x16x32_bf16 v[56:59], v[76:79], v[116:119], v[56:59]
	global_load_dwordx4 v[84:87], v172, s[0:1] offset:1024
	v_mfma_f32_16x16x32_bf16 v[40:43], v[76:79], v[120:123], v[40:43]
	global_load_dwordx4 v[100:103], v172, s[4:5] offset:1024
	v_mfma_f32_16x16x32_bf16 v[24:27], v[76:79], v[124:127], v[24:27]
	global_load_dwordx4 v[88:91], v173, s[0:1] offset:1024
	v_mfma_f32_16x16x32_bf16 v[4:7], v[76:79], v[128:131], v[4:7]
	global_load_dwordx4 v[104:107], v173, s[4:5] offset:1024
	v_mfma_f32_16x16x32_bf16 v[52:55], v[80:83], v[116:119], v[52:55]
	global_load_dwordx4 v[92:95], v183, s[0:1] offset:1024
	v_mfma_f32_16x16x32_bf16 v[36:39], v[80:83], v[120:123], v[36:39]
	global_load_dwordx4 v[108:111], v183, s[4:5] offset:1024
	v_mfma_f32_16x16x32_bf16 v[20:23], v[80:83], v[124:127], v[20:23]
	global_load_dwordx4 v[96:99], v2, s[0:1] offset:1024
	v_mfma_f32_16x16x32_bf16 v[8:11], v[80:83], v[128:131], v[8:11]
	global_load_dwordx4 v[112:115], v2, s[4:5] offset:1024
	s_waitcnt lgkmcnt(0)
	s_barrier
	v_mfma_f32_16x16x32_bf16 v[64:67], v[152:155], v[168:171], v[64:67]
	ds_read_b128 v[68:71], v176
	v_mfma_f32_16x16x32_bf16 v[48:51], v[152:155], v[240:243], v[48:51]
	ds_read_b128 v[116:119], v177 offset:32768
	v_mfma_f32_16x16x32_bf16 v[32:35], v[152:155], v[244:247], v[32:35]
	ds_read_b128 v[72:75], v176 offset:2048
	v_mfma_f32_16x16x32_bf16 v[16:19], v[152:155], v[248:251], v[16:19]
	ds_read_b128 v[120:123], v177 offset:34816
	v_mfma_f32_16x16x32_bf16 v[60:63], v[156:159], v[168:171], v[60:63]
	ds_read_b128 v[76:79], v176 offset:4096
	v_mfma_f32_16x16x32_bf16 v[44:47], v[156:159], v[240:243], v[44:47]
	ds_read_b128 v[124:127], v177 offset:36864
	v_mfma_f32_16x16x32_bf16 v[28:31], v[156:159], v[244:247], v[28:31]
	ds_read_b128 v[80:83], v176 offset:6144
	v_mfma_f32_16x16x32_bf16 v[12:15], v[156:159], v[248:251], v[12:15]
	ds_read_b128 v[128:131], v177 offset:38912
	v_mfma_f32_16x16x32_bf16 v[56:59], v[160:163], v[168:171], v[56:59]
	v_mfma_f32_16x16x32_bf16 v[40:43], v[160:163], v[240:243], v[40:43]
	v_mfma_f32_16x16x32_bf16 v[24:27], v[160:163], v[244:247], v[24:27]
	v_mfma_f32_16x16x32_bf16 v[4:7], v[160:163], v[248:251], v[4:7]
	v_mfma_f32_16x16x32_bf16 v[52:55], v[164:167], v[168:171], v[52:55]
	v_mfma_f32_16x16x32_bf16 v[36:39], v[164:167], v[240:243], v[36:39]
	v_mfma_f32_16x16x32_bf16 v[20:23], v[164:167], v[244:247], v[20:23]
	v_mfma_f32_16x16x32_bf16 v[8:11], v[164:167], v[248:251], v[8:11]
	s_waitcnt lgkmcnt(0)
	v_mfma_f32_16x16x32_bf16 v[64:67], v[68:71], v[116:119], v[64:67]
	ds_read_b128 v[152:155], v178
	s_waitcnt vmcnt(8)
	ds_write_b128 v174, v[184:187] offset:16384
	v_mfma_f32_16x16x32_bf16 v[48:51], v[68:71], v[120:123], v[48:51]
	ds_read_b128 v[168:171], v179 offset:32768
	ds_write_b128 v174, v[200:203] offset:49152
	v_mfma_f32_16x16x32_bf16 v[32:35], v[68:71], v[124:127], v[32:35]
	ds_read_b128 v[156:159], v178 offset:2048
	ds_write_b128 v174, v[188:191] offset:20480
	v_mfma_f32_16x16x32_bf16 v[16:19], v[68:71], v[128:131], v[16:19]
	ds_read_b128 v[240:243], v179 offset:34816
	ds_write_b128 v174, v[204:207] offset:53248
	v_mfma_f32_16x16x32_bf16 v[60:63], v[72:75], v[116:119], v[60:63]
	ds_read_b128 v[160:163], v178 offset:4096
	ds_write_b128 v174, v[192:195] offset:24576
	v_mfma_f32_16x16x32_bf16 v[44:47], v[72:75], v[120:123], v[44:47]
	ds_read_b128 v[244:247], v179 offset:36864
	ds_write_b128 v174, v[208:211] offset:57344
	v_mfma_f32_16x16x32_bf16 v[28:31], v[72:75], v[124:127], v[28:31]
	ds_read_b128 v[164:167], v178 offset:6144
	ds_write_b128 v174, v[196:199] offset:28672
	v_mfma_f32_16x16x32_bf16 v[12:15], v[72:75], v[128:131], v[12:15]
	ds_read_b128 v[248:251], v179 offset:38912
	ds_write_b128 v174, v[212:215] offset:61440
	v_mfma_f32_16x16x32_bf16 v[56:59], v[76:79], v[116:119], v[56:59]
	global_load_dwordx4 v[184:187], v172, s[0:1] offset:1152
	v_mfma_f32_16x16x32_bf16 v[40:43], v[76:79], v[120:123], v[40:43]
	global_load_dwordx4 v[200:203], v172, s[4:5] offset:1152
	v_mfma_f32_16x16x32_bf16 v[24:27], v[76:79], v[124:127], v[24:27]
	global_load_dwordx4 v[188:191], v173, s[0:1] offset:1152
	v_mfma_f32_16x16x32_bf16 v[4:7], v[76:79], v[128:131], v[4:7]
	global_load_dwordx4 v[204:207], v173, s[4:5] offset:1152
	v_mfma_f32_16x16x32_bf16 v[52:55], v[80:83], v[116:119], v[52:55]
	global_load_dwordx4 v[192:195], v183, s[0:1] offset:1152
	v_mfma_f32_16x16x32_bf16 v[36:39], v[80:83], v[120:123], v[36:39]
	global_load_dwordx4 v[208:211], v183, s[4:5] offset:1152
	v_mfma_f32_16x16x32_bf16 v[20:23], v[80:83], v[124:127], v[20:23]
	global_load_dwordx4 v[196:199], v2, s[0:1] offset:1152
	v_mfma_f32_16x16x32_bf16 v[8:11], v[80:83], v[128:131], v[8:11]
	global_load_dwordx4 v[212:215], v2, s[4:5] offset:1152
	s_waitcnt lgkmcnt(0)
	s_barrier
	v_mfma_f32_16x16x32_bf16 v[64:67], v[152:155], v[168:171], v[64:67]
	ds_read_b128 v[68:71], v176 offset:16384
	v_mfma_f32_16x16x32_bf16 v[48:51], v[152:155], v[240:243], v[48:51]
	ds_read_b128 v[116:119], v177 offset:49152
	v_mfma_f32_16x16x32_bf16 v[32:35], v[152:155], v[244:247], v[32:35]
	ds_read_b128 v[72:75], v176 offset:18432
	v_mfma_f32_16x16x32_bf16 v[16:19], v[152:155], v[248:251], v[16:19]
	ds_read_b128 v[120:123], v177 offset:51200
	v_mfma_f32_16x16x32_bf16 v[60:63], v[156:159], v[168:171], v[60:63]
	ds_read_b128 v[76:79], v176 offset:20480
	v_mfma_f32_16x16x32_bf16 v[44:47], v[156:159], v[240:243], v[44:47]
	ds_read_b128 v[124:127], v177 offset:53248
	v_mfma_f32_16x16x32_bf16 v[28:31], v[156:159], v[244:247], v[28:31]
	ds_read_b128 v[80:83], v176 offset:22528
	v_mfma_f32_16x16x32_bf16 v[12:15], v[156:159], v[248:251], v[12:15]
	ds_read_b128 v[128:131], v177 offset:55296
	v_mfma_f32_16x16x32_bf16 v[56:59], v[160:163], v[168:171], v[56:59]
	v_mfma_f32_16x16x32_bf16 v[40:43], v[160:163], v[240:243], v[40:43]
	v_mfma_f32_16x16x32_bf16 v[24:27], v[160:163], v[244:247], v[24:27]
	v_mfma_f32_16x16x32_bf16 v[4:7], v[160:163], v[248:251], v[4:7]
	v_mfma_f32_16x16x32_bf16 v[52:55], v[164:167], v[168:171], v[52:55]
	v_mfma_f32_16x16x32_bf16 v[36:39], v[164:167], v[240:243], v[36:39]
	v_mfma_f32_16x16x32_bf16 v[20:23], v[164:167], v[244:247], v[20:23]
	v_mfma_f32_16x16x32_bf16 v[8:11], v[164:167], v[248:251], v[8:11]
	s_waitcnt lgkmcnt(0)
	v_mfma_f32_16x16x32_bf16 v[64:67], v[68:71], v[116:119], v[64:67]
	ds_read_b128 v[152:155], v178 offset:16384
	s_waitcnt vmcnt(8)
	ds_write_b128 v174, v[84:87]
	v_mfma_f32_16x16x32_bf16 v[48:51], v[68:71], v[120:123], v[48:51]
	ds_read_b128 v[168:171], v179 offset:49152
	ds_write_b128 v174, v[100:103] offset:32768
	v_mfma_f32_16x16x32_bf16 v[32:35], v[68:71], v[124:127], v[32:35]
	ds_read_b128 v[156:159], v178 offset:18432
	ds_write_b128 v174, v[88:91] offset:4096
	v_mfma_f32_16x16x32_bf16 v[16:19], v[68:71], v[128:131], v[16:19]
	ds_read_b128 v[240:243], v179 offset:51200
	ds_write_b128 v174, v[104:107] offset:36864
	v_mfma_f32_16x16x32_bf16 v[60:63], v[72:75], v[116:119], v[60:63]
	ds_read_b128 v[160:163], v178 offset:20480
	ds_write_b128 v174, v[92:95] offset:8192
	v_mfma_f32_16x16x32_bf16 v[44:47], v[72:75], v[120:123], v[44:47]
	ds_read_b128 v[244:247], v179 offset:53248
	ds_write_b128 v174, v[108:111] offset:40960
	v_mfma_f32_16x16x32_bf16 v[28:31], v[72:75], v[124:127], v[28:31]
	ds_read_b128 v[164:167], v178 offset:22528
	ds_write_b128 v174, v[96:99] offset:12288
	v_mfma_f32_16x16x32_bf16 v[12:15], v[72:75], v[128:131], v[12:15]
	ds_read_b128 v[248:251], v179 offset:55296
	ds_write_b128 v174, v[112:115] offset:45056
	v_mfma_f32_16x16x32_bf16 v[56:59], v[76:79], v[116:119], v[56:59]
	global_load_dwordx4 v[84:87], v172, s[0:1] offset:1280
	v_mfma_f32_16x16x32_bf16 v[40:43], v[76:79], v[120:123], v[40:43]
	global_load_dwordx4 v[100:103], v172, s[4:5] offset:1280
	v_mfma_f32_16x16x32_bf16 v[24:27], v[76:79], v[124:127], v[24:27]
	global_load_dwordx4 v[88:91], v173, s[0:1] offset:1280
	v_mfma_f32_16x16x32_bf16 v[4:7], v[76:79], v[128:131], v[4:7]
	global_load_dwordx4 v[104:107], v173, s[4:5] offset:1280
	v_mfma_f32_16x16x32_bf16 v[52:55], v[80:83], v[116:119], v[52:55]
	global_load_dwordx4 v[92:95], v183, s[0:1] offset:1280
	v_mfma_f32_16x16x32_bf16 v[36:39], v[80:83], v[120:123], v[36:39]
	global_load_dwordx4 v[108:111], v183, s[4:5] offset:1280
	v_mfma_f32_16x16x32_bf16 v[20:23], v[80:83], v[124:127], v[20:23]
	global_load_dwordx4 v[96:99], v2, s[0:1] offset:1280
	v_mfma_f32_16x16x32_bf16 v[8:11], v[80:83], v[128:131], v[8:11]
	global_load_dwordx4 v[112:115], v2, s[4:5] offset:1280
	s_waitcnt lgkmcnt(0)
	s_barrier
	v_mfma_f32_16x16x32_bf16 v[64:67], v[152:155], v[168:171], v[64:67]
	ds_read_b128 v[68:71], v176
	v_mfma_f32_16x16x32_bf16 v[48:51], v[152:155], v[240:243], v[48:51]
	ds_read_b128 v[116:119], v177 offset:32768
	v_mfma_f32_16x16x32_bf16 v[32:35], v[152:155], v[244:247], v[32:35]
	ds_read_b128 v[72:75], v176 offset:2048
	v_mfma_f32_16x16x32_bf16 v[16:19], v[152:155], v[248:251], v[16:19]
	ds_read_b128 v[120:123], v177 offset:34816
	v_mfma_f32_16x16x32_bf16 v[60:63], v[156:159], v[168:171], v[60:63]
	ds_read_b128 v[76:79], v176 offset:4096
	v_mfma_f32_16x16x32_bf16 v[44:47], v[156:159], v[240:243], v[44:47]
	ds_read_b128 v[124:127], v177 offset:36864
	v_mfma_f32_16x16x32_bf16 v[28:31], v[156:159], v[244:247], v[28:31]
	ds_read_b128 v[80:83], v176 offset:6144
	v_mfma_f32_16x16x32_bf16 v[12:15], v[156:159], v[248:251], v[12:15]
	ds_read_b128 v[128:131], v177 offset:38912
	v_mfma_f32_16x16x32_bf16 v[56:59], v[160:163], v[168:171], v[56:59]
	v_mfma_f32_16x16x32_bf16 v[40:43], v[160:163], v[240:243], v[40:43]
	v_mfma_f32_16x16x32_bf16 v[24:27], v[160:163], v[244:247], v[24:27]
	v_mfma_f32_16x16x32_bf16 v[4:7], v[160:163], v[248:251], v[4:7]
	v_mfma_f32_16x16x32_bf16 v[52:55], v[164:167], v[168:171], v[52:55]
	v_mfma_f32_16x16x32_bf16 v[36:39], v[164:167], v[240:243], v[36:39]
	v_mfma_f32_16x16x32_bf16 v[20:23], v[164:167], v[244:247], v[20:23]
	v_mfma_f32_16x16x32_bf16 v[8:11], v[164:167], v[248:251], v[8:11]
	s_waitcnt lgkmcnt(0)
	v_mfma_f32_16x16x32_bf16 v[64:67], v[68:71], v[116:119], v[64:67]
	ds_read_b128 v[152:155], v178
	s_waitcnt vmcnt(8)
	ds_write_b128 v174, v[184:187] offset:16384
	v_mfma_f32_16x16x32_bf16 v[48:51], v[68:71], v[120:123], v[48:51]
	ds_read_b128 v[168:171], v179 offset:32768
	ds_write_b128 v174, v[200:203] offset:49152
	v_mfma_f32_16x16x32_bf16 v[32:35], v[68:71], v[124:127], v[32:35]
	ds_read_b128 v[156:159], v178 offset:2048
	ds_write_b128 v174, v[188:191] offset:20480
	v_mfma_f32_16x16x32_bf16 v[16:19], v[68:71], v[128:131], v[16:19]
	ds_read_b128 v[240:243], v179 offset:34816
	ds_write_b128 v174, v[204:207] offset:53248
	v_mfma_f32_16x16x32_bf16 v[60:63], v[72:75], v[116:119], v[60:63]
	ds_read_b128 v[160:163], v178 offset:4096
	ds_write_b128 v174, v[192:195] offset:24576
	v_mfma_f32_16x16x32_bf16 v[44:47], v[72:75], v[120:123], v[44:47]
	ds_read_b128 v[244:247], v179 offset:36864
	ds_write_b128 v174, v[208:211] offset:57344
	v_mfma_f32_16x16x32_bf16 v[28:31], v[72:75], v[124:127], v[28:31]
	ds_read_b128 v[164:167], v178 offset:6144
	ds_write_b128 v174, v[196:199] offset:28672
	v_mfma_f32_16x16x32_bf16 v[12:15], v[72:75], v[128:131], v[12:15]
	ds_read_b128 v[248:251], v179 offset:38912
	ds_write_b128 v174, v[212:215] offset:61440
	v_mfma_f32_16x16x32_bf16 v[56:59], v[76:79], v[116:119], v[56:59]
	global_load_dwordx4 v[184:187], v172, s[0:1] offset:1408
	v_mfma_f32_16x16x32_bf16 v[40:43], v[76:79], v[120:123], v[40:43]
	global_load_dwordx4 v[200:203], v172, s[4:5] offset:1408
	v_mfma_f32_16x16x32_bf16 v[24:27], v[76:79], v[124:127], v[24:27]
	global_load_dwordx4 v[188:191], v173, s[0:1] offset:1408
	v_mfma_f32_16x16x32_bf16 v[4:7], v[76:79], v[128:131], v[4:7]
	global_load_dwordx4 v[204:207], v173, s[4:5] offset:1408
	v_mfma_f32_16x16x32_bf16 v[52:55], v[80:83], v[116:119], v[52:55]
	global_load_dwordx4 v[192:195], v183, s[0:1] offset:1408
	v_mfma_f32_16x16x32_bf16 v[36:39], v[80:83], v[120:123], v[36:39]
	global_load_dwordx4 v[208:211], v183, s[4:5] offset:1408
	v_mfma_f32_16x16x32_bf16 v[20:23], v[80:83], v[124:127], v[20:23]
	global_load_dwordx4 v[196:199], v2, s[0:1] offset:1408
	v_mfma_f32_16x16x32_bf16 v[8:11], v[80:83], v[128:131], v[8:11]
	global_load_dwordx4 v[212:215], v2, s[4:5] offset:1408
	s_waitcnt lgkmcnt(0)
	s_barrier
	v_mfma_f32_16x16x32_bf16 v[64:67], v[152:155], v[168:171], v[64:67]
	ds_read_b128 v[68:71], v176 offset:16384
	v_mfma_f32_16x16x32_bf16 v[48:51], v[152:155], v[240:243], v[48:51]
	ds_read_b128 v[116:119], v177 offset:49152
	v_mfma_f32_16x16x32_bf16 v[32:35], v[152:155], v[244:247], v[32:35]
	ds_read_b128 v[72:75], v176 offset:18432
	v_mfma_f32_16x16x32_bf16 v[16:19], v[152:155], v[248:251], v[16:19]
	ds_read_b128 v[120:123], v177 offset:51200
	v_mfma_f32_16x16x32_bf16 v[60:63], v[156:159], v[168:171], v[60:63]
	ds_read_b128 v[76:79], v176 offset:20480
	v_mfma_f32_16x16x32_bf16 v[44:47], v[156:159], v[240:243], v[44:47]
	ds_read_b128 v[124:127], v177 offset:53248
	v_mfma_f32_16x16x32_bf16 v[28:31], v[156:159], v[244:247], v[28:31]
	ds_read_b128 v[80:83], v176 offset:22528
	v_mfma_f32_16x16x32_bf16 v[12:15], v[156:159], v[248:251], v[12:15]
	ds_read_b128 v[128:131], v177 offset:55296
	v_mfma_f32_16x16x32_bf16 v[56:59], v[160:163], v[168:171], v[56:59]
	v_mfma_f32_16x16x32_bf16 v[40:43], v[160:163], v[240:243], v[40:43]
	v_mfma_f32_16x16x32_bf16 v[24:27], v[160:163], v[244:247], v[24:27]
	v_mfma_f32_16x16x32_bf16 v[4:7], v[160:163], v[248:251], v[4:7]
	v_mfma_f32_16x16x32_bf16 v[52:55], v[164:167], v[168:171], v[52:55]
	v_mfma_f32_16x16x32_bf16 v[36:39], v[164:167], v[240:243], v[36:39]
	v_mfma_f32_16x16x32_bf16 v[20:23], v[164:167], v[244:247], v[20:23]
	v_mfma_f32_16x16x32_bf16 v[8:11], v[164:167], v[248:251], v[8:11]
	s_waitcnt lgkmcnt(0)
	v_mfma_f32_16x16x32_bf16 v[64:67], v[68:71], v[116:119], v[64:67]
	ds_read_b128 v[152:155], v178 offset:16384
	s_waitcnt vmcnt(8)
	ds_write_b128 v174, v[84:87]
	v_mfma_f32_16x16x32_bf16 v[48:51], v[68:71], v[120:123], v[48:51]
	ds_read_b128 v[168:171], v179 offset:49152
	ds_write_b128 v174, v[100:103] offset:32768
	v_mfma_f32_16x16x32_bf16 v[32:35], v[68:71], v[124:127], v[32:35]
	ds_read_b128 v[156:159], v178 offset:18432
	ds_write_b128 v174, v[88:91] offset:4096
	v_mfma_f32_16x16x32_bf16 v[16:19], v[68:71], v[128:131], v[16:19]
	ds_read_b128 v[240:243], v179 offset:51200
	ds_write_b128 v174, v[104:107] offset:36864
	v_mfma_f32_16x16x32_bf16 v[60:63], v[72:75], v[116:119], v[60:63]
	ds_read_b128 v[160:163], v178 offset:20480
	ds_write_b128 v174, v[92:95] offset:8192
	v_mfma_f32_16x16x32_bf16 v[44:47], v[72:75], v[120:123], v[44:47]
	ds_read_b128 v[244:247], v179 offset:53248
	ds_write_b128 v174, v[108:111] offset:40960
	v_mfma_f32_16x16x32_bf16 v[28:31], v[72:75], v[124:127], v[28:31]
	ds_read_b128 v[164:167], v178 offset:22528
	ds_write_b128 v174, v[96:99] offset:12288
	v_mfma_f32_16x16x32_bf16 v[12:15], v[72:75], v[128:131], v[12:15]
	ds_read_b128 v[248:251], v179 offset:55296
	ds_write_b128 v174, v[112:115] offset:45056
	v_mfma_f32_16x16x32_bf16 v[56:59], v[76:79], v[116:119], v[56:59]
	global_load_dwordx4 v[84:87], v172, s[0:1] offset:1536
	v_mfma_f32_16x16x32_bf16 v[40:43], v[76:79], v[120:123], v[40:43]
	global_load_dwordx4 v[100:103], v172, s[4:5] offset:1536
	v_mfma_f32_16x16x32_bf16 v[24:27], v[76:79], v[124:127], v[24:27]
	global_load_dwordx4 v[88:91], v173, s[0:1] offset:1536
	v_mfma_f32_16x16x32_bf16 v[4:7], v[76:79], v[128:131], v[4:7]
	global_load_dwordx4 v[104:107], v173, s[4:5] offset:1536
	v_mfma_f32_16x16x32_bf16 v[52:55], v[80:83], v[116:119], v[52:55]
	global_load_dwordx4 v[92:95], v183, s[0:1] offset:1536
	v_mfma_f32_16x16x32_bf16 v[36:39], v[80:83], v[120:123], v[36:39]
	global_load_dwordx4 v[108:111], v183, s[4:5] offset:1536
	v_mfma_f32_16x16x32_bf16 v[20:23], v[80:83], v[124:127], v[20:23]
	global_load_dwordx4 v[96:99], v2, s[0:1] offset:1536
	v_mfma_f32_16x16x32_bf16 v[8:11], v[80:83], v[128:131], v[8:11]
	global_load_dwordx4 v[112:115], v2, s[4:5] offset:1536
	s_waitcnt lgkmcnt(0)
	s_barrier
	v_mfma_f32_16x16x32_bf16 v[64:67], v[152:155], v[168:171], v[64:67]
	ds_read_b128 v[68:71], v176
	v_mfma_f32_16x16x32_bf16 v[48:51], v[152:155], v[240:243], v[48:51]
	ds_read_b128 v[116:119], v177 offset:32768
	v_mfma_f32_16x16x32_bf16 v[32:35], v[152:155], v[244:247], v[32:35]
	ds_read_b128 v[72:75], v176 offset:2048
	v_mfma_f32_16x16x32_bf16 v[16:19], v[152:155], v[248:251], v[16:19]
	ds_read_b128 v[120:123], v177 offset:34816
	v_mfma_f32_16x16x32_bf16 v[60:63], v[156:159], v[168:171], v[60:63]
	ds_read_b128 v[76:79], v176 offset:4096
	v_mfma_f32_16x16x32_bf16 v[44:47], v[156:159], v[240:243], v[44:47]
	ds_read_b128 v[124:127], v177 offset:36864
	v_mfma_f32_16x16x32_bf16 v[28:31], v[156:159], v[244:247], v[28:31]
	ds_read_b128 v[80:83], v176 offset:6144
	v_mfma_f32_16x16x32_bf16 v[12:15], v[156:159], v[248:251], v[12:15]
	ds_read_b128 v[128:131], v177 offset:38912
	v_mfma_f32_16x16x32_bf16 v[56:59], v[160:163], v[168:171], v[56:59]
	v_mfma_f32_16x16x32_bf16 v[40:43], v[160:163], v[240:243], v[40:43]
	v_mfma_f32_16x16x32_bf16 v[24:27], v[160:163], v[244:247], v[24:27]
	v_mfma_f32_16x16x32_bf16 v[4:7], v[160:163], v[248:251], v[4:7]
	v_mfma_f32_16x16x32_bf16 v[52:55], v[164:167], v[168:171], v[52:55]
	v_mfma_f32_16x16x32_bf16 v[36:39], v[164:167], v[240:243], v[36:39]
	v_mfma_f32_16x16x32_bf16 v[20:23], v[164:167], v[244:247], v[20:23]
	v_mfma_f32_16x16x32_bf16 v[8:11], v[164:167], v[248:251], v[8:11]
	s_waitcnt lgkmcnt(0)
	v_mfma_f32_16x16x32_bf16 v[64:67], v[68:71], v[116:119], v[64:67]
	ds_read_b128 v[152:155], v178
	s_waitcnt vmcnt(8)
	ds_write_b128 v174, v[184:187] offset:16384
	v_mfma_f32_16x16x32_bf16 v[48:51], v[68:71], v[120:123], v[48:51]
	ds_read_b128 v[168:171], v179 offset:32768
	ds_write_b128 v174, v[200:203] offset:49152
	v_mfma_f32_16x16x32_bf16 v[32:35], v[68:71], v[124:127], v[32:35]
	ds_read_b128 v[156:159], v178 offset:2048
	ds_write_b128 v174, v[188:191] offset:20480
	v_mfma_f32_16x16x32_bf16 v[16:19], v[68:71], v[128:131], v[16:19]
	ds_read_b128 v[240:243], v179 offset:34816
	ds_write_b128 v174, v[204:207] offset:53248
	v_mfma_f32_16x16x32_bf16 v[60:63], v[72:75], v[116:119], v[60:63]
	ds_read_b128 v[160:163], v178 offset:4096
	ds_write_b128 v174, v[192:195] offset:24576
	v_mfma_f32_16x16x32_bf16 v[44:47], v[72:75], v[120:123], v[44:47]
	ds_read_b128 v[244:247], v179 offset:36864
	ds_write_b128 v174, v[208:211] offset:57344
	v_mfma_f32_16x16x32_bf16 v[28:31], v[72:75], v[124:127], v[28:31]
	ds_read_b128 v[164:167], v178 offset:6144
	ds_write_b128 v174, v[196:199] offset:28672
	v_mfma_f32_16x16x32_bf16 v[12:15], v[72:75], v[128:131], v[12:15]
	ds_read_b128 v[248:251], v179 offset:38912
	ds_write_b128 v174, v[212:215] offset:61440
	v_mfma_f32_16x16x32_bf16 v[56:59], v[76:79], v[116:119], v[56:59]
	global_load_dwordx4 v[184:187], v172, s[0:1] offset:1664
	v_mfma_f32_16x16x32_bf16 v[40:43], v[76:79], v[120:123], v[40:43]
	global_load_dwordx4 v[200:203], v172, s[4:5] offset:1664
	v_mfma_f32_16x16x32_bf16 v[24:27], v[76:79], v[124:127], v[24:27]
	global_load_dwordx4 v[188:191], v173, s[0:1] offset:1664
	v_mfma_f32_16x16x32_bf16 v[4:7], v[76:79], v[128:131], v[4:7]
	global_load_dwordx4 v[204:207], v173, s[4:5] offset:1664
	v_mfma_f32_16x16x32_bf16 v[52:55], v[80:83], v[116:119], v[52:55]
	global_load_dwordx4 v[192:195], v183, s[0:1] offset:1664
	v_mfma_f32_16x16x32_bf16 v[36:39], v[80:83], v[120:123], v[36:39]
	global_load_dwordx4 v[208:211], v183, s[4:5] offset:1664
	v_mfma_f32_16x16x32_bf16 v[20:23], v[80:83], v[124:127], v[20:23]
	global_load_dwordx4 v[196:199], v2, s[0:1] offset:1664
	v_mfma_f32_16x16x32_bf16 v[8:11], v[80:83], v[128:131], v[8:11]
	global_load_dwordx4 v[212:215], v2, s[4:5] offset:1664
	s_waitcnt lgkmcnt(0)
	s_barrier
	v_mfma_f32_16x16x32_bf16 v[64:67], v[152:155], v[168:171], v[64:67]
	ds_read_b128 v[68:71], v176 offset:16384
	v_mfma_f32_16x16x32_bf16 v[48:51], v[152:155], v[240:243], v[48:51]
	ds_read_b128 v[116:119], v177 offset:49152
	v_mfma_f32_16x16x32_bf16 v[32:35], v[152:155], v[244:247], v[32:35]
	ds_read_b128 v[72:75], v176 offset:18432
	v_mfma_f32_16x16x32_bf16 v[16:19], v[152:155], v[248:251], v[16:19]
	ds_read_b128 v[120:123], v177 offset:51200
	v_mfma_f32_16x16x32_bf16 v[60:63], v[156:159], v[168:171], v[60:63]
	ds_read_b128 v[76:79], v176 offset:20480
	v_mfma_f32_16x16x32_bf16 v[44:47], v[156:159], v[240:243], v[44:47]
	ds_read_b128 v[124:127], v177 offset:53248
	v_mfma_f32_16x16x32_bf16 v[28:31], v[156:159], v[244:247], v[28:31]
	ds_read_b128 v[80:83], v176 offset:22528
	v_mfma_f32_16x16x32_bf16 v[12:15], v[156:159], v[248:251], v[12:15]
	ds_read_b128 v[128:131], v177 offset:55296
	v_mfma_f32_16x16x32_bf16 v[56:59], v[160:163], v[168:171], v[56:59]
	v_mfma_f32_16x16x32_bf16 v[40:43], v[160:163], v[240:243], v[40:43]
	v_mfma_f32_16x16x32_bf16 v[24:27], v[160:163], v[244:247], v[24:27]
	v_mfma_f32_16x16x32_bf16 v[4:7], v[160:163], v[248:251], v[4:7]
	v_mfma_f32_16x16x32_bf16 v[52:55], v[164:167], v[168:171], v[52:55]
	v_mfma_f32_16x16x32_bf16 v[36:39], v[164:167], v[240:243], v[36:39]
	v_mfma_f32_16x16x32_bf16 v[20:23], v[164:167], v[244:247], v[20:23]
	v_mfma_f32_16x16x32_bf16 v[8:11], v[164:167], v[248:251], v[8:11]
	s_waitcnt lgkmcnt(0)
	v_mfma_f32_16x16x32_bf16 v[64:67], v[68:71], v[116:119], v[64:67]
	ds_read_b128 v[152:155], v178 offset:16384
	s_waitcnt vmcnt(8)
	ds_write_b128 v174, v[84:87]
	v_mfma_f32_16x16x32_bf16 v[48:51], v[68:71], v[120:123], v[48:51]
	ds_read_b128 v[168:171], v179 offset:49152
	ds_write_b128 v174, v[100:103] offset:32768
	v_mfma_f32_16x16x32_bf16 v[32:35], v[68:71], v[124:127], v[32:35]
	ds_read_b128 v[156:159], v178 offset:18432
	ds_write_b128 v174, v[88:91] offset:4096
	v_mfma_f32_16x16x32_bf16 v[16:19], v[68:71], v[128:131], v[16:19]
	ds_read_b128 v[240:243], v179 offset:51200
	ds_write_b128 v174, v[104:107] offset:36864
	v_mfma_f32_16x16x32_bf16 v[60:63], v[72:75], v[116:119], v[60:63]
	ds_read_b128 v[160:163], v178 offset:20480
	ds_write_b128 v174, v[92:95] offset:8192
	v_mfma_f32_16x16x32_bf16 v[44:47], v[72:75], v[120:123], v[44:47]
	ds_read_b128 v[244:247], v179 offset:53248
	ds_write_b128 v174, v[108:111] offset:40960
	v_mfma_f32_16x16x32_bf16 v[28:31], v[72:75], v[124:127], v[28:31]
	ds_read_b128 v[164:167], v178 offset:22528
	ds_write_b128 v174, v[96:99] offset:12288
	v_mfma_f32_16x16x32_bf16 v[12:15], v[72:75], v[128:131], v[12:15]
	ds_read_b128 v[248:251], v179 offset:55296
	ds_write_b128 v174, v[112:115] offset:45056
	v_mfma_f32_16x16x32_bf16 v[56:59], v[76:79], v[116:119], v[56:59]
	global_load_dwordx4 v[84:87], v172, s[0:1] offset:1792
	v_mfma_f32_16x16x32_bf16 v[40:43], v[76:79], v[120:123], v[40:43]
	global_load_dwordx4 v[100:103], v172, s[4:5] offset:1792
	v_mfma_f32_16x16x32_bf16 v[24:27], v[76:79], v[124:127], v[24:27]
	global_load_dwordx4 v[88:91], v173, s[0:1] offset:1792
	v_mfma_f32_16x16x32_bf16 v[4:7], v[76:79], v[128:131], v[4:7]
	global_load_dwordx4 v[104:107], v173, s[4:5] offset:1792
	v_mfma_f32_16x16x32_bf16 v[52:55], v[80:83], v[116:119], v[52:55]
	global_load_dwordx4 v[92:95], v183, s[0:1] offset:1792
	v_mfma_f32_16x16x32_bf16 v[36:39], v[80:83], v[120:123], v[36:39]
	global_load_dwordx4 v[108:111], v183, s[4:5] offset:1792
	v_mfma_f32_16x16x32_bf16 v[20:23], v[80:83], v[124:127], v[20:23]
	global_load_dwordx4 v[96:99], v2, s[0:1] offset:1792
	v_mfma_f32_16x16x32_bf16 v[8:11], v[80:83], v[128:131], v[8:11]
	global_load_dwordx4 v[112:115], v2, s[4:5] offset:1792
	s_waitcnt lgkmcnt(0)
	s_barrier
	v_mfma_f32_16x16x32_bf16 v[64:67], v[152:155], v[168:171], v[64:67]
	ds_read_b128 v[68:71], v176
	v_mfma_f32_16x16x32_bf16 v[48:51], v[152:155], v[240:243], v[48:51]
	ds_read_b128 v[116:119], v177 offset:32768
	v_mfma_f32_16x16x32_bf16 v[32:35], v[152:155], v[244:247], v[32:35]
	ds_read_b128 v[72:75], v176 offset:2048
	v_mfma_f32_16x16x32_bf16 v[16:19], v[152:155], v[248:251], v[16:19]
	ds_read_b128 v[120:123], v177 offset:34816
	v_mfma_f32_16x16x32_bf16 v[60:63], v[156:159], v[168:171], v[60:63]
	ds_read_b128 v[76:79], v176 offset:4096
	v_mfma_f32_16x16x32_bf16 v[44:47], v[156:159], v[240:243], v[44:47]
	ds_read_b128 v[124:127], v177 offset:36864
	v_mfma_f32_16x16x32_bf16 v[28:31], v[156:159], v[244:247], v[28:31]
	ds_read_b128 v[80:83], v176 offset:6144
	v_mfma_f32_16x16x32_bf16 v[12:15], v[156:159], v[248:251], v[12:15]
	ds_read_b128 v[128:131], v177 offset:38912
	v_mfma_f32_16x16x32_bf16 v[56:59], v[160:163], v[168:171], v[56:59]
	v_mfma_f32_16x16x32_bf16 v[40:43], v[160:163], v[240:243], v[40:43]
	v_mfma_f32_16x16x32_bf16 v[24:27], v[160:163], v[244:247], v[24:27]
	v_mfma_f32_16x16x32_bf16 v[4:7], v[160:163], v[248:251], v[4:7]
	v_mfma_f32_16x16x32_bf16 v[52:55], v[164:167], v[168:171], v[52:55]
	v_mfma_f32_16x16x32_bf16 v[36:39], v[164:167], v[240:243], v[36:39]
	v_mfma_f32_16x16x32_bf16 v[20:23], v[164:167], v[244:247], v[20:23]
	v_mfma_f32_16x16x32_bf16 v[8:11], v[164:167], v[248:251], v[8:11]
	s_waitcnt lgkmcnt(0)
	v_mfma_f32_16x16x32_bf16 v[64:67], v[68:71], v[116:119], v[64:67]
	ds_read_b128 v[152:155], v178
	s_waitcnt vmcnt(8)
	ds_write_b128 v174, v[184:187] offset:16384
	v_mfma_f32_16x16x32_bf16 v[48:51], v[68:71], v[120:123], v[48:51]
	ds_read_b128 v[168:171], v179 offset:32768
	ds_write_b128 v174, v[200:203] offset:49152
	v_mfma_f32_16x16x32_bf16 v[32:35], v[68:71], v[124:127], v[32:35]
	ds_read_b128 v[156:159], v178 offset:2048
	ds_write_b128 v174, v[188:191] offset:20480
	v_mfma_f32_16x16x32_bf16 v[16:19], v[68:71], v[128:131], v[16:19]
	ds_read_b128 v[240:243], v179 offset:34816
	ds_write_b128 v174, v[204:207] offset:53248
	v_mfma_f32_16x16x32_bf16 v[60:63], v[72:75], v[116:119], v[60:63]
	ds_read_b128 v[160:163], v178 offset:4096
	ds_write_b128 v174, v[192:195] offset:24576
	v_mfma_f32_16x16x32_bf16 v[44:47], v[72:75], v[120:123], v[44:47]
	ds_read_b128 v[244:247], v179 offset:36864
	ds_write_b128 v174, v[208:211] offset:57344
	v_mfma_f32_16x16x32_bf16 v[28:31], v[72:75], v[124:127], v[28:31]
	ds_read_b128 v[164:167], v178 offset:6144
	ds_write_b128 v174, v[196:199] offset:28672
	v_mfma_f32_16x16x32_bf16 v[12:15], v[72:75], v[128:131], v[12:15]
	ds_read_b128 v[248:251], v179 offset:38912
	ds_write_b128 v174, v[212:215] offset:61440
	v_mfma_f32_16x16x32_bf16 v[56:59], v[76:79], v[116:119], v[56:59]
	global_load_dwordx4 v[184:187], v172, s[0:1] offset:1920
	v_mfma_f32_16x16x32_bf16 v[40:43], v[76:79], v[120:123], v[40:43]
	global_load_dwordx4 v[200:203], v172, s[4:5] offset:1920
	v_mfma_f32_16x16x32_bf16 v[24:27], v[76:79], v[124:127], v[24:27]
	global_load_dwordx4 v[188:191], v173, s[0:1] offset:1920
	v_mfma_f32_16x16x32_bf16 v[4:7], v[76:79], v[128:131], v[4:7]
	global_load_dwordx4 v[204:207], v173, s[4:5] offset:1920
	v_mfma_f32_16x16x32_bf16 v[52:55], v[80:83], v[116:119], v[52:55]
	global_load_dwordx4 v[192:195], v183, s[0:1] offset:1920
	v_mfma_f32_16x16x32_bf16 v[36:39], v[80:83], v[120:123], v[36:39]
	global_load_dwordx4 v[208:211], v183, s[4:5] offset:1920
	v_mfma_f32_16x16x32_bf16 v[20:23], v[80:83], v[124:127], v[20:23]
	global_load_dwordx4 v[196:199], v2, s[0:1] offset:1920
	v_mfma_f32_16x16x32_bf16 v[8:11], v[80:83], v[128:131], v[8:11]
	global_load_dwordx4 v[212:215], v2, s[4:5] offset:1920
	s_waitcnt lgkmcnt(0)
	s_barrier
	v_mfma_f32_16x16x32_bf16 v[64:67], v[152:155], v[168:171], v[64:67]
	ds_read_b128 v[68:71], v176 offset:16384
	v_mfma_f32_16x16x32_bf16 v[48:51], v[152:155], v[240:243], v[48:51]
	ds_read_b128 v[116:119], v177 offset:49152
	v_mfma_f32_16x16x32_bf16 v[32:35], v[152:155], v[244:247], v[32:35]
	ds_read_b128 v[72:75], v176 offset:18432
	v_mfma_f32_16x16x32_bf16 v[16:19], v[152:155], v[248:251], v[16:19]
	ds_read_b128 v[120:123], v177 offset:51200
	v_mfma_f32_16x16x32_bf16 v[60:63], v[156:159], v[168:171], v[60:63]
	ds_read_b128 v[76:79], v176 offset:20480
	v_mfma_f32_16x16x32_bf16 v[44:47], v[156:159], v[240:243], v[44:47]
	ds_read_b128 v[124:127], v177 offset:53248
	v_mfma_f32_16x16x32_bf16 v[28:31], v[156:159], v[244:247], v[28:31]
	ds_read_b128 v[80:83], v176 offset:22528
	v_mfma_f32_16x16x32_bf16 v[12:15], v[156:159], v[248:251], v[12:15]
	ds_read_b128 v[128:131], v177 offset:55296
	v_mfma_f32_16x16x32_bf16 v[56:59], v[160:163], v[168:171], v[56:59]
	v_mfma_f32_16x16x32_bf16 v[40:43], v[160:163], v[240:243], v[40:43]
	v_mfma_f32_16x16x32_bf16 v[24:27], v[160:163], v[244:247], v[24:27]
	v_mfma_f32_16x16x32_bf16 v[4:7], v[160:163], v[248:251], v[4:7]
	v_mfma_f32_16x16x32_bf16 v[52:55], v[164:167], v[168:171], v[52:55]
	v_mfma_f32_16x16x32_bf16 v[36:39], v[164:167], v[240:243], v[36:39]
	v_mfma_f32_16x16x32_bf16 v[20:23], v[164:167], v[244:247], v[20:23]
	v_mfma_f32_16x16x32_bf16 v[8:11], v[164:167], v[248:251], v[8:11]
	s_waitcnt lgkmcnt(0)
	v_readlane_b32 s11, v252, 0
	s_add_i32 s11, s36, s11
	s_cmpk_lt_u32 s11, 0x3b8
	s_cselect_b32 s11, s11, s36
	s_bfe_u32 s0, s11, 0xf0001
	s_mul_i32 s0, s0, 0x89af
	s_lshr_b32 s0, s0, 22
	s_mul_i32 s1, s0, 0xee
	s_sub_i32 s1, s11, s1
	s_mul_i32 s4, s1, 37
	s_lshr_b32 s5, s4, 8
	s_sub_i32 s5, s1, s5
	s_bfe_u32 s5, s5, 0x70001
	s_bfe_u32 s4, s4, 0x80008
	s_add_i32 s5, s5, s4
	s_bfe_u32 s4, s5, 0x60002
	s_mul_i32 s5, s4, 7
	s_sub_i32 s1, s1, s5
	s_sub_i32 s5, 33, s4
	s_bitcmp1_b32 s0, 0
	s_cselect_b32 s4, s5, s4
	s_and_b32 s6, s1, 0xff
	s_mul_i32 s0, s0, 7
	s_add_i32 s6, s6, s0
	v_readlane_b32 s0, v252, 8
	s_add_i32 s7, s0, s4
	s_lshl_b32 s0, s6, 18
	s_add_u32 s0, s66, s0
	s_addc_u32 s1, s67, 0
	s_lshl_b32 s4, s7, 18
	s_add_u32 s4, s20, s4
	s_addc_u32 s5, s21, 0
	v_mfma_f32_16x16x32_bf16 v[64:67], v[68:71], v[116:119], v[64:67]
	ds_read_b128 v[152:155], v178 offset:16384
	s_waitcnt vmcnt(8)
	ds_write_b128 v174, v[84:87]
	v_mfma_f32_16x16x32_bf16 v[48:51], v[68:71], v[120:123], v[48:51]
	ds_read_b128 v[168:171], v179 offset:49152
	ds_write_b128 v174, v[100:103] offset:32768
	v_mfma_f32_16x16x32_bf16 v[32:35], v[68:71], v[124:127], v[32:35]
	ds_read_b128 v[156:159], v178 offset:18432
	ds_write_b128 v174, v[88:91] offset:4096
	v_mfma_f32_16x16x32_bf16 v[16:19], v[68:71], v[128:131], v[16:19]
	ds_read_b128 v[240:243], v179 offset:51200
	ds_write_b128 v174, v[104:107] offset:36864
	v_mfma_f32_16x16x32_bf16 v[60:63], v[72:75], v[116:119], v[60:63]
	ds_read_b128 v[160:163], v178 offset:20480
	ds_write_b128 v174, v[92:95] offset:8192
	v_mfma_f32_16x16x32_bf16 v[44:47], v[72:75], v[120:123], v[44:47]
	ds_read_b128 v[244:247], v179 offset:53248
	ds_write_b128 v174, v[108:111] offset:40960
	v_mfma_f32_16x16x32_bf16 v[28:31], v[72:75], v[124:127], v[28:31]
	ds_read_b128 v[164:167], v178 offset:22528
	ds_write_b128 v174, v[96:99] offset:12288
	v_mfma_f32_16x16x32_bf16 v[12:15], v[72:75], v[128:131], v[12:15]
	ds_read_b128 v[248:251], v179 offset:55296
	ds_write_b128 v174, v[112:115] offset:45056
	v_mfma_f32_16x16x32_bf16 v[56:59], v[76:79], v[116:119], v[56:59]
	global_load_dwordx4 v[84:87], v172, s[0:1]
	v_mfma_f32_16x16x32_bf16 v[40:43], v[76:79], v[120:123], v[40:43]
	global_load_dwordx4 v[100:103], v172, s[4:5]
	v_mfma_f32_16x16x32_bf16 v[24:27], v[76:79], v[124:127], v[24:27]
	global_load_dwordx4 v[88:91], v173, s[0:1]
	v_mfma_f32_16x16x32_bf16 v[4:7], v[76:79], v[128:131], v[4:7]
	global_load_dwordx4 v[104:107], v173, s[4:5]
	v_mfma_f32_16x16x32_bf16 v[52:55], v[80:83], v[116:119], v[52:55]
	global_load_dwordx4 v[92:95], v183, s[0:1]
	v_mfma_f32_16x16x32_bf16 v[36:39], v[80:83], v[120:123], v[36:39]
	global_load_dwordx4 v[108:111], v183, s[4:5]
	v_mfma_f32_16x16x32_bf16 v[20:23], v[80:83], v[124:127], v[20:23]
	global_load_dwordx4 v[96:99], v2, s[0:1]
	v_mfma_f32_16x16x32_bf16 v[8:11], v[80:83], v[128:131], v[8:11]
	global_load_dwordx4 v[112:115], v2, s[4:5]
	s_waitcnt lgkmcnt(0)
	s_barrier
	v_mfma_f32_16x16x32_bf16 v[64:67], v[152:155], v[168:171], v[64:67]
	ds_read_b128 v[68:71], v176
	v_mfma_f32_16x16x32_bf16 v[48:51], v[152:155], v[240:243], v[48:51]
	ds_read_b128 v[116:119], v177 offset:32768
	v_mfma_f32_16x16x32_bf16 v[32:35], v[152:155], v[244:247], v[32:35]
	ds_read_b128 v[72:75], v176 offset:2048
	v_mfma_f32_16x16x32_bf16 v[16:19], v[152:155], v[248:251], v[16:19]
	ds_read_b128 v[120:123], v177 offset:34816
	v_mfma_f32_16x16x32_bf16 v[60:63], v[156:159], v[168:171], v[60:63]
	ds_read_b128 v[76:79], v176 offset:4096
	v_mfma_f32_16x16x32_bf16 v[44:47], v[156:159], v[240:243], v[44:47]
	ds_read_b128 v[124:127], v177 offset:36864
	v_mfma_f32_16x16x32_bf16 v[28:31], v[156:159], v[244:247], v[28:31]
	ds_read_b128 v[80:83], v176 offset:6144
	v_mfma_f32_16x16x32_bf16 v[12:15], v[156:159], v[248:251], v[12:15]
	ds_read_b128 v[128:131], v177 offset:38912
	v_mfma_f32_16x16x32_bf16 v[56:59], v[160:163], v[168:171], v[56:59]
	v_mfma_f32_16x16x32_bf16 v[40:43], v[160:163], v[240:243], v[40:43]
	v_mfma_f32_16x16x32_bf16 v[24:27], v[160:163], v[244:247], v[24:27]
	v_mfma_f32_16x16x32_bf16 v[4:7], v[160:163], v[248:251], v[4:7]
	v_mfma_f32_16x16x32_bf16 v[52:55], v[164:167], v[168:171], v[52:55]
	v_mfma_f32_16x16x32_bf16 v[36:39], v[164:167], v[240:243], v[36:39]
	v_mfma_f32_16x16x32_bf16 v[20:23], v[164:167], v[244:247], v[20:23]
	v_mfma_f32_16x16x32_bf16 v[8:11], v[164:167], v[248:251], v[8:11]
	s_waitcnt lgkmcnt(0)
	v_mfma_f32_16x16x32_bf16 v[64:67], v[68:71], v[116:119], v[64:67]
	ds_read_b128 v[152:155], v178
	s_waitcnt vmcnt(8)
	ds_write_b128 v174, v[184:187] offset:16384
	v_mfma_f32_16x16x32_bf16 v[48:51], v[68:71], v[120:123], v[48:51]
	ds_read_b128 v[168:171], v179 offset:32768
	ds_write_b128 v174, v[200:203] offset:49152
	v_mfma_f32_16x16x32_bf16 v[32:35], v[68:71], v[124:127], v[32:35]
	ds_read_b128 v[156:159], v178 offset:2048
	ds_write_b128 v174, v[188:191] offset:20480
	v_mfma_f32_16x16x32_bf16 v[16:19], v[68:71], v[128:131], v[16:19]
	ds_read_b128 v[240:243], v179 offset:34816
	ds_write_b128 v174, v[204:207] offset:53248
	v_mfma_f32_16x16x32_bf16 v[60:63], v[72:75], v[116:119], v[60:63]
	ds_read_b128 v[160:163], v178 offset:4096
	ds_write_b128 v174, v[192:195] offset:24576
	v_mfma_f32_16x16x32_bf16 v[44:47], v[72:75], v[120:123], v[44:47]
	ds_read_b128 v[244:247], v179 offset:36864
	ds_write_b128 v174, v[208:211] offset:57344
	v_mfma_f32_16x16x32_bf16 v[28:31], v[72:75], v[124:127], v[28:31]
	ds_read_b128 v[164:167], v178 offset:6144
	ds_write_b128 v174, v[196:199] offset:28672
	v_mfma_f32_16x16x32_bf16 v[12:15], v[72:75], v[128:131], v[12:15]
	ds_read_b128 v[248:251], v179 offset:38912
	ds_write_b128 v174, v[212:215] offset:61440
	v_mfma_f32_16x16x32_bf16 v[56:59], v[76:79], v[116:119], v[56:59]
	global_load_dwordx4 v[184:187], v172, s[0:1] offset:128
	v_mfma_f32_16x16x32_bf16 v[40:43], v[76:79], v[120:123], v[40:43]
	global_load_dwordx4 v[200:203], v172, s[4:5] offset:128
	v_mfma_f32_16x16x32_bf16 v[24:27], v[76:79], v[124:127], v[24:27]
	global_load_dwordx4 v[188:191], v173, s[0:1] offset:128
	v_mfma_f32_16x16x32_bf16 v[4:7], v[76:79], v[128:131], v[4:7]
	global_load_dwordx4 v[204:207], v173, s[4:5] offset:128
	v_mfma_f32_16x16x32_bf16 v[52:55], v[80:83], v[116:119], v[52:55]
	global_load_dwordx4 v[192:195], v183, s[0:1] offset:128
	v_mfma_f32_16x16x32_bf16 v[36:39], v[80:83], v[120:123], v[36:39]
	global_load_dwordx4 v[208:211], v183, s[4:5] offset:128
	v_mfma_f32_16x16x32_bf16 v[20:23], v[80:83], v[124:127], v[20:23]
	global_load_dwordx4 v[196:199], v2, s[0:1] offset:128
	v_mfma_f32_16x16x32_bf16 v[8:11], v[80:83], v[128:131], v[8:11]
	global_load_dwordx4 v[212:215], v2, s[4:5] offset:128
	s_waitcnt lgkmcnt(0)
	s_barrier
	v_mfma_f32_16x16x32_bf16 v[64:67], v[152:155], v[168:171], v[64:67]
	ds_read_b128 v[68:71], v176 offset:16384
	v_mfma_f32_16x16x32_bf16 v[48:51], v[152:155], v[240:243], v[48:51]
	ds_read_b128 v[116:119], v177 offset:49152
	v_mfma_f32_16x16x32_bf16 v[32:35], v[152:155], v[244:247], v[32:35]
	ds_read_b128 v[72:75], v176 offset:18432
	v_mfma_f32_16x16x32_bf16 v[16:19], v[152:155], v[248:251], v[16:19]
	ds_read_b128 v[120:123], v177 offset:51200
	v_mfma_f32_16x16x32_bf16 v[60:63], v[156:159], v[168:171], v[60:63]
	ds_read_b128 v[76:79], v176 offset:20480
	v_mfma_f32_16x16x32_bf16 v[44:47], v[156:159], v[240:243], v[44:47]
	ds_read_b128 v[124:127], v177 offset:53248
	v_mfma_f32_16x16x32_bf16 v[28:31], v[156:159], v[244:247], v[28:31]
	ds_read_b128 v[80:83], v176 offset:22528
	v_mfma_f32_16x16x32_bf16 v[12:15], v[156:159], v[248:251], v[12:15]
	ds_read_b128 v[128:131], v177 offset:55296
	v_mfma_f32_16x16x32_bf16 v[56:59], v[160:163], v[168:171], v[56:59]
	v_mfma_f32_16x16x32_bf16 v[40:43], v[160:163], v[240:243], v[40:43]
	v_mfma_f32_16x16x32_bf16 v[24:27], v[160:163], v[244:247], v[24:27]
	v_mfma_f32_16x16x32_bf16 v[4:7], v[160:163], v[248:251], v[4:7]
	v_mfma_f32_16x16x32_bf16 v[52:55], v[164:167], v[168:171], v[52:55]
	v_mfma_f32_16x16x32_bf16 v[36:39], v[164:167], v[240:243], v[36:39]
	v_mfma_f32_16x16x32_bf16 v[20:23], v[164:167], v[244:247], v[20:23]
	v_mfma_f32_16x16x32_bf16 v[8:11], v[164:167], v[248:251], v[8:11]
	s_waitcnt lgkmcnt(0)
	v_mfma_f32_16x16x32_bf16 v[64:67], v[68:71], v[116:119], v[64:67]
	ds_read_b128 v[152:155], v178 offset:16384
	v_mfma_f32_16x16x32_bf16 v[48:51], v[68:71], v[120:123], v[48:51]
	ds_read_b128 v[168:171], v179 offset:49152
	v_mfma_f32_16x16x32_bf16 v[32:35], v[68:71], v[124:127], v[32:35]
	ds_read_b128 v[156:159], v178 offset:18432
	v_mfma_f32_16x16x32_bf16 v[16:19], v[68:71], v[128:131], v[16:19]
	ds_read_b128 v[240:243], v179 offset:51200
	v_mfma_f32_16x16x32_bf16 v[60:63], v[72:75], v[116:119], v[60:63]
	ds_read_b128 v[160:163], v178 offset:20480
	v_mfma_f32_16x16x32_bf16 v[44:47], v[72:75], v[120:123], v[44:47]
	ds_read_b128 v[244:247], v179 offset:53248
	v_mfma_f32_16x16x32_bf16 v[28:31], v[72:75], v[124:127], v[28:31]
	ds_read_b128 v[164:167], v178 offset:22528
	v_mfma_f32_16x16x32_bf16 v[12:15], v[72:75], v[128:131], v[12:15]
	ds_read_b128 v[248:251], v179 offset:55296
	v_mfma_f32_16x16x32_bf16 v[56:59], v[76:79], v[116:119], v[56:59]
	v_mfma_f32_16x16x32_bf16 v[40:43], v[76:79], v[120:123], v[40:43]
	v_mfma_f32_16x16x32_bf16 v[24:27], v[76:79], v[124:127], v[24:27]
	v_mfma_f32_16x16x32_bf16 v[4:7], v[76:79], v[128:131], v[4:7]
	v_mfma_f32_16x16x32_bf16 v[52:55], v[80:83], v[116:119], v[52:55]
	v_mfma_f32_16x16x32_bf16 v[36:39], v[80:83], v[120:123], v[36:39]
	v_mfma_f32_16x16x32_bf16 v[20:23], v[80:83], v[124:127], v[20:23]
	v_mfma_f32_16x16x32_bf16 v[8:11], v[80:83], v[128:131], v[8:11]
	s_waitcnt lgkmcnt(0)
	s_barrier
	v_mfma_f32_16x16x32_bf16 v[64:67], v[152:155], v[168:171], v[64:67]
	v_mfma_f32_16x16x32_bf16 v[48:51], v[152:155], v[240:243], v[48:51]
	v_mfma_f32_16x16x32_bf16 v[32:35], v[152:155], v[244:247], v[32:35]
	v_mfma_f32_16x16x32_bf16 v[16:19], v[152:155], v[248:251], v[16:19]
	v_mfma_f32_16x16x32_bf16 v[60:63], v[156:159], v[168:171], v[60:63]
	v_mfma_f32_16x16x32_bf16 v[44:47], v[156:159], v[240:243], v[44:47]
	v_mfma_f32_16x16x32_bf16 v[28:31], v[156:159], v[244:247], v[28:31]
	v_mfma_f32_16x16x32_bf16 v[12:15], v[156:159], v[248:251], v[12:15]
	v_mfma_f32_16x16x32_bf16 v[56:59], v[160:163], v[168:171], v[56:59]
	v_mfma_f32_16x16x32_bf16 v[40:43], v[160:163], v[240:243], v[40:43]
	v_mfma_f32_16x16x32_bf16 v[24:27], v[160:163], v[244:247], v[24:27]
	v_mfma_f32_16x16x32_bf16 v[4:7], v[160:163], v[248:251], v[4:7]
	v_mfma_f32_16x16x32_bf16 v[52:55], v[164:167], v[168:171], v[52:55]
	v_mfma_f32_16x16x32_bf16 v[36:39], v[164:167], v[240:243], v[36:39]
	v_mfma_f32_16x16x32_bf16 v[20:23], v[164:167], v[244:247], v[20:23]
	v_mfma_f32_16x16x32_bf16 v[8:11], v[164:167], v[248:251], v[8:11]
	s_nop 7
	s_nop 7
